# hgrn output pass: entering state copied HU->LDS by LDS-DMA as soon as the buffer is free instead of a register load waited for right before the chain
# speedup vs baseline: 1.0463x; 1.0009x over previous
; #define LAS __attribute__((address_space(3)))
; #define LDS_WAIT() asm volatile("s_waitcnt lgkmcnt(0)" ::: "memory")
; __device__ __forceinline__ float bf1(bf16 h) { return __uint_as_float(((unsigned)h) << 16); }
; __device__ __forceinline__ float sigmf(float v) { return __builtin_amdgcn_rcpf(1.0f + __builtin_amdgcn_exp2f(-1.4426950408889634f * v)); }
; template <bool OUT> __device__ __forceinline__ HRaw hgrn_load(const PA& a, int bh, int c, int wave, int lane) {
;     const bf16* pr = (const bf16*)(a.ws + WS_PROJ) + ((size_t)(bh >> 2) * T + (size_t)c * 128 + wave * 16 + (lane >> 3)) * DIN + (bh & 3) * 64 + (lane & 7) * 8;
;     HRaw r;
; #pragma unroll
;     for (int k = 0; k < 2; ++k) { r.f[k] = *(const v4u*)(pr + (size_t)(8 * k) * DIN + 256); r.v[k] = *(const v4u*)(pr + (size_t)(8 * k) * DIN + 512);
;         if (OUT) { r.q[k] = *(const v4u*)(pr + (size_t)(8 * k) * DIN); r.g[k] = *(const v4u*)(pr + (size_t)(8 * k) * DIN + 768); } }
;     return r;
; }
; template <bool OUT> __device__ __forceinline__ void hgrn_item2(const PA& a, LAS unsigned char* lds, int layer, int bh, int c, int wave, int lane, const HRaw& raw) {
;     ...
;     __syncthreads();
;     {
;         const int rr = lane >> 3, cc = (lane & 7) * 8;
; #pragma unroll
;         for (int k = 0; k < 2; ++k) { *(LAS v4u*)(RF + (rr + 8 * k) * 72 + cc) = raw.f[k]; *(LAS v4u*)(RV + (rr + 8 * k) * 72 + cc) = raw.v[k]; if (OUT) *(LAS v4u*)(RQ + (rr + 8 * k) * 72 + cc) = raw.q[k]; }
;         LDS_WAIT();
;         const float lb = (layer == 0) ? 0.f : sigmf(a.in[4][256 + h * 64 + lane] - a.in[4][h * 64 + lane]);
;         u16 fr[16], vr[16], qr[16];
; #pragma unroll
;         for (int t = 0; t < 16; ++t) { fr[t] = RF[t * 72 + lane]; vr[t] = RV[t * 72 + lane]; if (OUT) qr[t] = RQ[t * 72 + lane]; }
;         LDS_WAIT();
;         float cum[16], kk[16]; float run = 0.f;
; #pragma unroll
;         for (int t = 0; t < 16; ++t) { const float sg = sigmf(bf1(fr[t])); const float f = lb + (1.f - lb) * sg; kk[t] = (1.f - lb) * (1.f - sg); run += fmaxf(__logf(f), -69.f); cum[t] = run; }
.LBB0_708:
	s_ashr_i32 s0, s8, 7
	s_and_b32 s12, s8, 31
	s_ashr_i32 s1, s0, 31
	s_lshl_b64 s[0:1], s[0:1], 13
	s_lshl_b32 s9, s12, 7
	s_or_b32 s14, s0, s9
	s_mov_b32 s15, s1
	v_lshl_add_u64 v[198:199], s[14:15], 0, v[188:189]
	v_mov_b64_e32 v[0:1], s[60:61]
	v_mad_u64_u32 v[2:3], s[14:15], v198, s93, v[0:1]
	s_ashr_i32 s11, s8, 5
	v_mov_b32_e32 v4, v3
	v_mad_u64_u32 v[4:5], s[14:15], v199, s93, v[4:5]
	s_lshl_b32 s9, s11, 7
	v_mov_b32_e32 v3, v4
	s_and_b32 s62, s9, 0x180
	s_xor_b32 s9, s12, 63
	v_lshl_add_u64 v[2:3], v[2:3], 0, s[62:63]
	s_lshl_b32 s10, s9, 7
	v_lshl_add_u64 v[2:3], v[2:3], 0, v[220:221]
	s_mov_b32 s13, 0xe000
	s_or_b32 s0, s0, s10
	global_load_dwordx4 v[40:43], v[2:3], off offset:512
	global_load_dwordx4 v[44:47], v[2:3], off offset:1024
	global_load_dwordx4 v[48:51], v[2:3], off
	global_load_dwordx4 v[32:35], v[2:3], off offset:1536
	v_add_co_u32_e32 v2, vcc, s13, v2
	v_lshl_add_u64 v[196:197], s[0:1], 0, v[188:189]
	s_nop 0
	v_addc_co_u32_e32 v3, vcc, 0, v3, vcc
	v_mad_u64_u32 v[0:1], s[0:1], v196, s93, v[0:1]
	global_load_dwordx4 v[52:55], v[2:3], off offset:512
	global_load_dwordx4 v[56:59], v[2:3], off offset:1024
	global_load_dwordx4 v[60:63], v[2:3], off
	global_load_dwordx4 v[36:39], v[2:3], off offset:1536
	v_mov_b32_e32 v2, v1
	v_mad_u64_u32 v[2:3], s[0:1], v197, s93, v[2:3]
	v_mov_b32_e32 v1, v2
	v_lshl_add_u64 v[0:1], v[0:1], 0, s[62:63]
	v_lshl_add_u64 v[4:5], v[0:1], 0, v[220:221]
	global_load_dwordx4 v[8:11], v[4:5], off offset:512
	global_load_dwordx4 v[12:15], v[4:5], off offset:1024
	global_load_dwordx4 v[16:19], v[4:5], off
	global_load_dwordx4 v[0:3], v[4:5], off offset:1536
	v_add_co_u32_e32 v4, vcc, s13, v4
	s_and_b32 s10, s11, 3
	s_nop 0
	v_addc_co_u32_e32 v5, vcc, 0, v5, vcc
	global_load_dwordx4 v[20:23], v[4:5], off offset:512
	global_load_dwordx4 v[24:27], v[4:5], off offset:1024
	global_load_dwordx4 v[28:31], v[4:5], off
	s_nop 0
	global_load_dwordx4 v[4:7], v[4:5], off offset:1536
	s_waitcnt vmcnt(63) expcnt(7) lgkmcnt(15)
	s_barrier
	v_readfirstlane_b32 s98, v206
	s_add_i32 m0, s98, 0x18000
	s_lshl_b32 s98, s11, 6
	s_or_b32 s98, s98, s12
	s_ashr_i32 s99, s98, 31
	s_lshl_b64 s[98:99], s[98:99], 14
	s_add_u32 s98, s89, s98
	s_addc_u32 s99, s25, s99
	global_load_lds_dwordx4 v224, s[98:99]
	s_add_i32 m0, m0, 0x400
	s_nop 0
	global_load_lds_dwordx4 v240, s[98:99]
	s_andn2_b64 vcc, exec, s[4:5]
	s_waitcnt vmcnt(15)
	ds_write_b128 v201, v[40:43]
	s_waitcnt vmcnt(14)
	ds_write_b128 v201, v[44:47] offset:2304
	s_waitcnt vmcnt(13)
	ds_write_b128 v201, v[48:51] offset:4608
	s_waitcnt vmcnt(11)
	ds_write_b128 v201, v[52:55] offset:1152
	s_waitcnt vmcnt(10)
	ds_write_b128 v201, v[56:59] offset:3456
	s_waitcnt vmcnt(9)
	ds_write_b128 v201, v[60:63] offset:5760
	s_waitcnt lgkmcnt(0)
	v_cndmask_b32_e64 v41, 0, 1, s[4:5]
	v_mov_b32_e32 v40, 0
	v_cmp_ne_u32_e64 s[48:49], 1, v41
	v_mov_b32_e32 v51, 0
	s_cbranch_vccnz .LBB0_710
	v_lshlrev_b32_e32 v41, 5, v234
	v_add_u32_e32 v41, 0x1e000, v41
	ds_read_b32 v51, v41 offset:16
	s_waitcnt lgkmcnt(0)
.LBB0_710:
	ds_read_u16 v41, v202 offset:2304
	ds_read_u16 v42, v202 offset:2448
	ds_read_u16 v43, v202 offset:2592
	ds_read_u16 v44, v202 offset:2736
	ds_read_u16 v45, v202 offset:2880
	ds_read_u16 v46, v202 offset:3024
	ds_read_u16 v47, v202 offset:3168
	ds_read_u16 v48, v202 offset:3312
	s_waitcnt lgkmcnt(6)
	v_lshl_or_b32 v42, v42, 16, v41
	s_waitcnt lgkmcnt(4)
	v_lshl_or_b32 v43, v44, 16, v43
	s_waitcnt lgkmcnt(2)
	v_lshl_or_b32 v44, v46, 16, v45
	s_waitcnt lgkmcnt(0)
	v_lshl_or_b32 v45, v48, 16, v47
	ds_read_u16 v41, v202 offset:3456
	ds_read_u16 v46, v202 offset:3600
	ds_read_u16 v47, v202 offset:3744
	ds_read_u16 v48, v202 offset:3888
	ds_read_u16 v49, v202 offset:4032
	ds_read_u16 v50, v202 offset:4176
	ds_read_u16 v52, v202 offset:4320
	ds_read_u16 v53, v202 offset:4464
	s_waitcnt lgkmcnt(6)
	v_lshl_or_b32 v46, v46, 16, v41
	ds_read_u16 v41, v202
	ds_read_u16 v54, v202 offset:144
	ds_read_u16 v55, v202 offset:288
	ds_read_u16 v56, v202 offset:432
	ds_read_u16 v57, v202 offset:576
	ds_read_u16 v58, v202 offset:720
	ds_read_u16 v59, v202 offset:864
	ds_read_u16 v60, v202 offset:1008
	s_waitcnt lgkmcnt(7)
	v_lshlrev_b32_e32 v41, 16, v41
	v_mul_f32_e32 v41, 0xbfb8aa3b, v41
	v_exp_f32_e32 v41, v41
	v_lshl_or_b32 v47, v48, 16, v47
	v_lshl_or_b32 v48, v50, 16, v49
	v_lshl_or_b32 v49, v53, 16, v52
	v_add_f32_e32 v41, 1.0, v41
	v_rcp_f32_e32 v52, v41
	v_sub_f32_e32 v50, 1.0, v51
	s_waitcnt lgkmcnt(6)
	v_lshlrev_b32_e32 v54, 16, v54
	v_mul_f32_e32 v54, 0xbfb8aa3b, v54
	v_fma_f32 v41, v50, v52, v51
	v_cmp_gt_f32_e32 vcc, s27, v41
	v_exp_f32_e32 v54, v54
	s_waitcnt lgkmcnt(5)
	v_lshlrev_b32_e32 v55, 16, v55
	v_cndmask_b32_e64 v53, 0, 32, vcc
	v_ldexp_f32 v41, v41, v53
	v_log_f32_e32 v53, v41
	v_add_f32_e32 v54, 1.0, v54
	v_rcp_f32_e32 v54, v54
	v_mul_f32_e32 v55, 0xbfb8aa3b, v55
	v_mul_f32_e32 v66, 0x3f317217, v53
	v_fma_f32 v66, v53, s80, -v66
	v_fmac_f32_e32 v66, 0x3377d1cf, v53
	v_fmac_f32_e32 v66, 0x3f317217, v53
	v_cmp_lt_f32_e64 s[0:1], |v53|, s81
	v_fma_f32 v68, v50, v54, v51
	v_exp_f32_e32 v55, v55
	v_cndmask_b32_e64 v53, v53, v66, s[0:1]
	v_cndmask_b32_e32 v66, 0, v238, vcc
	v_cmp_gt_f32_e32 vcc, s27, v68
	v_sub_f32_e32 v53, v53, v66
	v_max_f32_e32 v53, 0xc28a0000, v53
	v_cndmask_b32_e64 v76, 0, 32, vcc
	v_ldexp_f32 v68, v68, v76
	v_log_f32_e32 v68, v68
	v_add_f32_e32 v76, 0, v53
	s_waitcnt lgkmcnt(4)
	v_lshlrev_b32_e32 v56, 16, v56
	v_mul_f32_e32 v56, 0xbfb8aa3b, v56
	v_mul_f32_e32 v53, 0x3f317217, v68
	v_fma_f32 v66, v68, s80, -v53
	v_add_f32_e32 v53, 1.0, v55
	v_rcp_f32_e32 v53, v53
	v_fmac_f32_e32 v66, 0x3377d1cf, v68
	v_fmac_f32_e32 v66, 0x3f317217, v68
	v_cmp_lt_f32_e64 s[0:1], |v68|, s81
	v_exp_f32_e32 v56, v56
	s_waitcnt lgkmcnt(3)
; __device__ __forceinline__ float bf1(bf16 h) { return __uint_as_float(((unsigned)h) << 16); }
; __device__ __forceinline__ float sigmf(float v) { return __builtin_amdgcn_rcpf(1.0f + __builtin_amdgcn_exp2f(-1.4426950408889634f * v)); }
; template <bool OUT> __device__ __forceinline__ void hgrn_item2(const PA& a, LAS unsigned char* lds, int layer, int bh, int c, int wave, int lane, const HRaw& raw) {
;     ...
;         float cum[16], kk[16]; float run = 0.f;
; #pragma unroll
;         for (int t = 0; t < 16; ++t) { const float sg = sigmf(bf1(fr[t])); const float f = lb + (1.f - lb) * sg; kk[t] = (1.f - lb) * (1.f - sg); run += fmaxf(__logf(f), -69.f); cum[t] = run; }
	v_lshlrev_b32_e32 v57, 16, v57
	v_cndmask_b32_e64 v55, v68, v66, s[0:1]
	v_fma_f32 v68, v50, v53, v51
	v_cndmask_b32_e32 v66, 0, v238, vcc
	v_cmp_gt_f32_e32 vcc, s27, v68
	v_sub_f32_e32 v55, v55, v66
	v_max_f32_e32 v55, 0xc28a0000, v55
	v_cndmask_b32_e64 v77, 0, 32, vcc
	v_ldexp_f32 v68, v68, v77
	v_log_f32_e32 v68, v68
	v_add_f32_e32 v77, v76, v55
	v_mul_f32_e32 v57, 0xbfb8aa3b, v57
	v_exp_f32_e32 v57, v57
	v_mul_f32_e32 v55, 0x3f317217, v68
	v_fma_f32 v66, v68, s80, -v55
	v_add_f32_e32 v55, 1.0, v56
	v_rcp_f32_e32 v55, v55
	v_fmac_f32_e32 v66, 0x3377d1cf, v68
	v_fmac_f32_e32 v66, 0x3f317217, v68
	v_cmp_lt_f32_e64 s[0:1], |v68|, s81
	s_waitcnt lgkmcnt(2)
	v_lshlrev_b32_e32 v58, 16, v58
	v_mul_f32_e32 v58, 0xbfb8aa3b, v58
	v_cndmask_b32_e64 v56, v68, v66, s[0:1]
	v_fma_f32 v68, v50, v55, v51
	v_cndmask_b32_e32 v66, 0, v238, vcc
	v_cmp_gt_f32_e32 vcc, s27, v68
	v_sub_f32_e32 v56, v56, v66
	v_max_f32_e32 v56, 0xc28a0000, v56
	v_cndmask_b32_e64 v78, 0, 32, vcc
	v_ldexp_f32 v68, v68, v78
	v_log_f32_e32 v68, v68
	v_add_f32_e32 v78, v77, v56
	v_exp_f32_e32 v58, v58
	s_waitcnt lgkmcnt(1)
	v_lshlrev_b32_e32 v59, 16, v59
	v_mul_f32_e32 v56, 0x3f317217, v68
	v_fma_f32 v66, v68, s80, -v56
	v_add_f32_e32 v56, 1.0, v57
	v_rcp_f32_e32 v56, v56
	v_fmac_f32_e32 v66, 0x3377d1cf, v68
	v_fmac_f32_e32 v66, 0x3f317217, v68
	v_cmp_lt_f32_e64 s[0:1], |v68|, s81
	v_add_f32_e32 v58, 1.0, v58
	v_rcp_f32_e32 v58, v58
	v_cndmask_b32_e64 v57, v68, v66, s[0:1]
	v_fma_f32 v68, v50, v56, v51
	v_cndmask_b32_e32 v66, 0, v238, vcc
	v_cmp_gt_f32_e32 vcc, s27, v68
	v_sub_f32_e32 v57, v57, v66
	v_max_f32_e32 v57, 0xc28a0000, v57
	v_cndmask_b32_e64 v79, 0, 32, vcc
	v_ldexp_f32 v68, v68, v79
	v_log_f32_e32 v68, v68
	v_add_f32_e32 v79, v78, v57
	v_cndmask_b32_e32 v66, 0, v238, vcc
	v_mul_f32_e32 v59, 0xbfb8aa3b, v59
	v_mul_f32_e32 v57, 0x3f317217, v68
	v_fma_f32 v57, v68, s80, -v57
	v_fmac_f32_e32 v57, 0x3377d1cf, v68
	v_fmac_f32_e32 v57, 0x3f317217, v68
	v_cmp_lt_f32_e64 s[0:1], |v68|, s81
	v_exp_f32_e32 v59, v59
	s_waitcnt lgkmcnt(0)
	v_lshlrev_b32_e32 v60, 16, v60
	v_cndmask_b32_e64 v57, v68, v57, s[0:1]
	v_fma_f32 v68, v50, v58, v51
	v_cmp_gt_f32_e32 vcc, s27, v68
	v_sub_f32_e32 v57, v57, v66
	v_max_f32_e32 v57, 0xc28a0000, v57
	v_cndmask_b32_e64 v80, 0, 32, vcc
	v_ldexp_f32 v68, v68, v80
	v_log_f32_e32 v68, v68
	v_add_f32_e32 v80, v79, v57
	v_mul_f32_e32 v60, 0xbfb8aa3b, v60
	v_exp_f32_e32 v60, v60
	v_mul_f32_e32 v57, 0x3f317217, v68
	v_fma_f32 v66, v68, s80, -v57
	v_add_f32_e32 v57, 1.0, v59
	v_rcp_f32_e32 v57, v57
	v_fmac_f32_e32 v66, 0x3377d1cf, v68
	v_fmac_f32_e32 v66, 0x3f317217, v68
	v_cmp_lt_f32_e64 s[0:1], |v68|, s81
	ds_read_u16 v61, v202 offset:1152
	ds_read_u16 v62, v202 offset:1296
	ds_read_u16 v63, v202 offset:1440
	ds_read_u16 v64, v202 offset:1584
	ds_read_u16 v65, v202 offset:1728
	ds_read_u16 v67, v202 offset:1872
	ds_read_u16 v85, v202 offset:2016
	ds_read_u16 v90, v202 offset:2160
	v_cndmask_b32_e64 v59, v68, v66, s[0:1]
	v_fma_f32 v68, v50, v57, v51
	v_cndmask_b32_e32 v66, 0, v238, vcc
	v_cmp_gt_f32_e32 vcc, s27, v68
	v_sub_f32_e32 v59, v59, v66
	v_max_f32_e32 v59, 0xc28a0000, v59
	v_cndmask_b32_e64 v81, 0, 32, vcc
	v_ldexp_f32 v68, v68, v81
	v_log_f32_e32 v68, v68
	v_add_f32_e32 v81, v80, v59
	s_waitcnt lgkmcnt(7)
	v_lshlrev_b32_e32 v61, 16, v61
	v_mul_f32_e32 v61, 0xbfb8aa3b, v61
	v_mul_f32_e32 v59, 0x3f317217, v68
	v_fma_f32 v66, v68, s80, -v59
	v_add_f32_e32 v59, 1.0, v60
	v_rcp_f32_e32 v59, v59
	v_fmac_f32_e32 v66, 0x3377d1cf, v68
	v_fmac_f32_e32 v66, 0x3f317217, v68
	v_cmp_lt_f32_e64 s[0:1], |v68|, s81
	v_exp_f32_e32 v61, v61
	s_waitcnt lgkmcnt(6)
	v_lshlrev_b32_e32 v62, 16, v62
	v_cndmask_b32_e64 v60, v68, v66, s[0:1]
	v_fma_f32 v68, v50, v59, v51
	v_cndmask_b32_e32 v66, 0, v238, vcc
	v_cmp_gt_f32_e32 vcc, s27, v68
	v_sub_f32_e32 v60, v60, v66
	v_max_f32_e32 v60, 0xc28a0000, v60
	v_cndmask_b32_e64 v82, 0, 32, vcc
	v_ldexp_f32 v68, v68, v82
	v_log_f32_e32 v68, v68
	v_add_f32_e32 v82, v81, v60
	v_mul_f32_e32 v62, 0xbfb8aa3b, v62
	v_exp_f32_e32 v62, v62
	v_mul_f32_e32 v60, 0x3f317217, v68
	v_fma_f32 v66, v68, s80, -v60
	v_add_f32_e32 v60, 1.0, v61
	v_rcp_f32_e32 v60, v60
	v_fmac_f32_e32 v66, 0x3377d1cf, v68
	v_fmac_f32_e32 v66, 0x3f317217, v68
	v_cmp_lt_f32_e64 s[0:1], |v68|, s81
	v_add_f32_e32 v62, 1.0, v62
	v_rcp_f32_e32 v62, v62
	v_cndmask_b32_e64 v61, v68, v66, s[0:1]
	v_fma_f32 v68, v50, v60, v51
	v_cndmask_b32_e32 v66, 0, v238, vcc
	v_cmp_gt_f32_e32 vcc, s27, v68
	v_sub_f32_e32 v61, v61, v66
	v_max_f32_e32 v61, 0xc28a0000, v61
	v_cndmask_b32_e64 v83, 0, 32, vcc
	v_ldexp_f32 v68, v68, v83
	v_log_f32_e32 v83, v68
	v_add_f32_e32 v68, v82, v61
	v_cndmask_b32_e32 v66, 0, v238, vcc
	s_waitcnt lgkmcnt(5)
	v_lshlrev_b32_e32 v63, 16, v63
	v_mul_f32_e32 v61, 0x3f317217, v83
	v_fma_f32 v61, v83, s80, -v61
	v_fmac_f32_e32 v61, 0x3377d1cf, v83
	v_fmac_f32_e32 v61, 0x3f317217, v83
	v_cmp_lt_f32_e64 s[0:1], |v83|, s81
	v_mul_f32_e32 v63, 0xbfb8aa3b, v63
	v_exp_f32_e32 v63, v63
	v_cndmask_b32_e64 v61, v83, v61, s[0:1]
	v_fma_f32 v83, v50, v62, v51
	v_cmp_gt_f32_e32 vcc, s27, v83
	v_sub_f32_e32 v61, v61, v66
	v_max_f32_e32 v61, 0xc28a0000, v61
	v_cndmask_b32_e64 v84, 0, 32, vcc
	v_ldexp_f32 v83, v83, v84
	v_log_f32_e32 v84, v83
	v_add_f32_e32 v83, v68, v61
	s_waitcnt lgkmcnt(4)
	v_lshlrev_b32_e32 v64, 16, v64
	v_mul_f32_e32 v64, 0xbfb8aa3b, v64
	v_mul_f32_e32 v61, 0x3f317217, v84
	v_fma_f32 v66, v84, s80, -v61
	v_add_f32_e32 v61, 1.0, v63
	v_rcp_f32_e32 v61, v61
	v_fmac_f32_e32 v66, 0x3377d1cf, v84
	v_fmac_f32_e32 v66, 0x3f317217, v84
	v_cmp_lt_f32_e64 s[0:1], |v84|, s81
	v_exp_f32_e32 v64, v64
	s_waitcnt lgkmcnt(3)
; #define LDS_WAIT() asm volatile("s_waitcnt lgkmcnt(0)" ::: "memory")
; __device__ __forceinline__ float bf1(bf16 h) { return __uint_as_float(((unsigned)h) << 16); }
; __device__ __forceinline__ float sigmf(float v) { return __builtin_amdgcn_rcpf(1.0f + __builtin_amdgcn_exp2f(-1.4426950408889634f * v)); }
; template <bool OUT> __device__ __forceinline__ void hgrn_item2(const PA& a, LAS unsigned char* lds, int layer, int bh, int c, int wave, int lane, const HRaw& raw) {
;     ...
;         for (int t = 0; t < 16; ++t) { fr[t] = RF[t * 72 + lane]; vr[t] = RV[t * 72 + lane]; if (OUT) qr[t] = RQ[t * 72 + lane]; }
;         LDS_WAIT();
;         float cum[16], kk[16]; float run = 0.f;
; #pragma unroll
;         for (int t = 0; t < 16; ++t) { const float sg = sigmf(bf1(fr[t])); const float f = lb + (1.f - lb) * sg; kk[t] = (1.f - lb) * (1.f - sg); run += fmaxf(__logf(f), -69.f); cum[t] = run; }
;         const float cl = cum[15], c7 = cum[7];
	v_lshlrev_b32_e32 v65, 16, v65
	v_cndmask_b32_e64 v63, v84, v66, s[0:1]
	v_fma_f32 v84, v50, v61, v51
	v_cndmask_b32_e32 v66, 0, v238, vcc
	v_cmp_gt_f32_e32 vcc, s27, v84
	v_sub_f32_e32 v63, v63, v66
	v_max_f32_e32 v63, 0xc28a0000, v63
	v_cndmask_b32_e64 v86, 0, 32, vcc
	v_ldexp_f32 v84, v84, v86
	v_log_f32_e32 v86, v84
	v_add_f32_e32 v84, v83, v63
	v_mul_f32_e32 v65, 0xbfb8aa3b, v65
	v_exp_f32_e32 v65, v65
	v_mul_f32_e32 v63, 0x3f317217, v86
	v_fma_f32 v66, v86, s80, -v63
	v_add_f32_e32 v63, 1.0, v64
	v_rcp_f32_e32 v63, v63
	v_fmac_f32_e32 v66, 0x3377d1cf, v86
	v_fmac_f32_e32 v66, 0x3f317217, v86
	v_cmp_lt_f32_e64 s[0:1], |v86|, s81
	v_add_f32_e32 v65, 1.0, v65
	ds_read_u16 v75, v202 offset:4608
	ds_read_u16 v74, v202 offset:4752
	ds_read_u16 v73, v202 offset:4896
	ds_read_u16 v72, v202 offset:5040
	ds_read_u16 v71, v202 offset:5184
	ds_read_u16 v70, v202 offset:5328
	ds_read_u16 v69, v202 offset:5472
	ds_read_u16 v41, v202 offset:5616
	v_cndmask_b32_e64 v64, v86, v66, s[0:1]
	v_fma_f32 v86, v50, v63, v51
	v_cndmask_b32_e32 v66, 0, v238, vcc
	v_cmp_gt_f32_e32 vcc, s27, v86
	v_sub_f32_e32 v64, v64, v66
	v_max_f32_e32 v64, 0xc28a0000, v64
	v_cndmask_b32_e64 v87, 0, 32, vcc
	v_ldexp_f32 v86, v86, v87
	v_log_f32_e32 v87, v86
	v_add_f32_e32 v86, v84, v64
	v_rcp_f32_e32 v66, v65
	v_cndmask_b32_e32 v65, 0, v238, vcc
	v_mul_f32_e32 v64, 0x3f317217, v87
	v_fma_f32 v64, v87, s80, -v64
	v_fmac_f32_e32 v64, 0x3377d1cf, v87
	v_fmac_f32_e32 v64, 0x3f317217, v87
	v_cmp_lt_f32_e64 s[0:1], |v87|, s81
	ds_read_u16 v116, v202 offset:5760
	ds_read_u16 v117, v202 offset:5904
	ds_read_u16 v118, v202 offset:6048
	ds_read_u16 v119, v202 offset:6192
	ds_read_u16 v95, v202 offset:6336
	ds_read_u16 v94, v202 offset:6480
	ds_read_u16 v93, v202 offset:6624
	ds_read_u16 v91, v202 offset:6768
	v_cndmask_b32_e64 v64, v87, v64, s[0:1]
	v_sub_f32_e32 v64, v64, v65
	s_waitcnt lgkmcnt(14)
	v_lshlrev_b32_e32 v65, 16, v67
	v_fma_f32 v87, v50, v66, v51
	v_mul_f32_e32 v65, 0xbfb8aa3b, v65
	v_cmp_gt_f32_e32 vcc, s27, v87
	v_exp_f32_e32 v65, v65
	v_max_f32_e32 v64, 0xc28a0000, v64
	v_cndmask_b32_e64 v88, 0, 32, vcc
	v_ldexp_f32 v87, v87, v88
	v_log_f32_e32 v88, v87
	v_add_f32_e32 v65, 1.0, v65
	v_rcp_f32_e32 v96, v65
	v_add_f32_e32 v87, v86, v64
	v_mul_f32_e32 v64, 0x3f317217, v88
	v_fma_f32 v64, v88, s80, -v64
	v_fmac_f32_e32 v64, 0x3377d1cf, v88
	v_fma_f32 v67, v50, v96, v51
	v_fmac_f32_e32 v64, 0x3f317217, v88
	v_cmp_lt_f32_e64 s[0:1], |v88|, s81
	v_cndmask_b32_e32 v65, 0, v238, vcc
	v_cmp_gt_f32_e32 vcc, s27, v67
	v_cndmask_b32_e64 v64, v88, v64, s[0:1]
	v_sub_f32_e32 v64, v64, v65
	v_cndmask_b32_e64 v88, 0, 32, vcc
	v_ldexp_f32 v67, v67, v88
	v_lshlrev_b32_e32 v65, 16, v85
	v_log_f32_e32 v89, v67
	v_mul_f32_e32 v65, 0xbfb8aa3b, v65
	v_exp_f32_e32 v65, v65
	v_max_f32_e32 v64, 0xc28a0000, v64
	v_add_f32_e32 v88, v87, v64
	v_mul_f32_e32 v64, 0x3f317217, v89
	v_fma_f32 v64, v89, s80, -v64
	v_add_f32_e32 v65, 1.0, v65
	v_fmac_f32_e32 v64, 0x3377d1cf, v89
	v_rcp_f32_e32 v67, v65
	v_fmac_f32_e32 v64, 0x3f317217, v89
	v_cmp_lt_f32_e64 s[0:1], |v89|, s81
	v_cndmask_b32_e32 v65, 0, v238, vcc
	v_fma_f32 v85, v50, v67, v51
	v_cndmask_b32_e64 v64, v89, v64, s[0:1]
	v_sub_f32_e32 v64, v64, v65
	v_lshlrev_b32_e32 v65, 16, v90
	v_mul_f32_e32 v65, 0xbfb8aa3b, v65
	v_cmp_gt_f32_e32 vcc, s27, v85
	v_exp_f32_e32 v65, v65
	v_max_f32_e32 v64, 0xc28a0000, v64
	v_cndmask_b32_e64 v89, 0, 32, vcc
	v_ldexp_f32 v85, v85, v89
	v_log_f32_e32 v85, v85
	v_add_f32_e32 v65, 1.0, v65
	v_rcp_f32_e32 v97, v65
	v_add_f32_e32 v89, v88, v64
	v_mul_f32_e32 v64, 0x3f317217, v85
	v_fma_f32 v64, v85, s80, -v64
	v_fmac_f32_e32 v64, 0x3377d1cf, v85
	v_fmac_f32_e32 v51, v50, v97
	v_fmac_f32_e32 v64, 0x3f317217, v85
	v_cmp_lt_f32_e64 s[0:1], |v85|, s81
	v_cndmask_b32_e32 v65, 0, v238, vcc
	v_cmp_gt_f32_e32 vcc, s27, v51
	v_cndmask_b32_e64 v64, v85, v64, s[0:1]
	v_sub_f32_e32 v64, v64, v65
	v_cndmask_b32_e64 v85, 0, 32, vcc
	v_ldexp_f32 v51, v51, v85
	v_log_f32_e32 v51, v51
	v_max_f32_e32 v64, 0xc28a0000, v64
	v_add_f32_e32 v90, v89, v64
	s_waitcnt lgkmcnt(0)
	v_mul_f32_e32 v64, 0x3f317217, v51
	v_fma_f32 v64, v51, s80, -v64
	v_fmac_f32_e32 v64, 0x3377d1cf, v51
	v_fmac_f32_e32 v64, 0x3f317217, v51
	v_cmp_lt_f32_e64 s[0:1], |v51|, s81
	v_pk_add_f32 v[52:53], v[52:53], 1.0 op_sel_hi:[1,0] neg_lo:[1,0] neg_hi:[1,0]
	v_pk_add_f32 v[56:57], v[56:57], 1.0 op_sel_hi:[1,0] neg_lo:[1,0] neg_hi:[1,0]
	v_cndmask_b32_e64 v51, v51, v64, s[0:1]
	v_cndmask_b32_e32 v64, 0, v238, vcc
	v_sub_f32_e32 v51, v51, v64
	v_max_f32_e32 v51, 0xc28a0000, v51
	v_add_f32_e32 v85, v90, v51
	v_mul_f32_e32 v51, 0x3fb8aa3b, v85
	v_mul_f32_e32 v64, 0x3fb8aa3b, v68
	v_exp_f32_e32 v51, v51
	v_exp_f32_e32 v64, v64
	v_sub_f32_e32 v92, v85, v68
	v_lshlrev_b32_e32 v75, 16, v75
	s_waitcnt lgkmcnt(8)
; #define LAS __attribute__((address_space(3)))
; __device__ __forceinline__ unsigned f2bf(float f) { unsigned u = __builtin_bit_cast(unsigned, f); return (u + 0x7fffu + ((u >> 16) & 1u)) >> 16; }
; __device__ __forceinline__ float bf1(bf16 h) { return __uint_as_float(((unsigned)h) << 16); }
; __device__ __forceinline__ float siluf(float v) { return v * sigmf(v); }
; __device__ __forceinline__ bf16x8 pk8(const float* v) { v4u w = {pk2(v[0], v[1]), pk2(v[2], v[3]), pk2(v[4], v[5]), pk2(v[6], v[7])}; return __builtin_bit_cast(bf16x8, w); }
; template <bool OUT> __device__ __forceinline__ void hgrn_item2(const PA& a, LAS unsigned char* lds, int layer, int bh, int c, int wave, int lane, const HRaw& raw) {
;     ...
;         DL[lane] = __expf(cl);
;         if (OUT) E7L[lane] = __expf(c7); else DALL[wave * 64 + lane] = cl;
;         float kh[16];
; #pragma unroll
;         for (int t = 0; t < 16; ++t) kh[t] = kk[t] * __expf(cl - cum[t]);
;         *(LAS bf16x8*)(KHT + lane * 24) = pk8(kh); *(LAS bf16x8*)(KHT + lane * 24 + 8) = pk8(kh + 8);
;         { v4u w0 = {(unsigned)vr[0] | ((unsigned)vr[1] << 16), (unsigned)vr[2] | ((unsigned)vr[3] << 16), (unsigned)vr[4] | ((unsigned)vr[5] << 16), (unsigned)vr[6] | ((unsigned)vr[7] << 16)};
;           v4u w1 = {(unsigned)vr[8] | ((unsigned)vr[9] << 16), (unsigned)vr[10] | ((unsigned)vr[11] << 16), (unsigned)vr[12] | ((unsigned)vr[13] << 16), (unsigned)vr[14] | ((unsigned)vr[15] << 16)};
;           *(LAS v4u*)(VT + lane * 24) = w0; *(LAS v4u*)(VT + lane * 24 + 8) = w1; }
;         if (OUT) {
; #pragma unroll
;             for (int t = 0; t < 16; ++t) {
;                 QT[t * 72 + lane] = (bf16)f2bf(siluf(bf1(qr[t])) * __expf(fminf(cum[t] - c7, 60.f)));
;                 KT[t * 72 + lane] = (bf16)f2bf(kk[t] * __expf(fminf(c7 - cum[t], 60.f)));
;             }
	v_lshlrev_b32_e32 v41, 16, v41
	ds_write2st64_b32 v203, v51, v64 offset0:45 offset1:46
	v_sub_f32_e32 v51, v85, v76
	v_mul_f32_e32 v51, 0x3fb8aa3b, v51
	v_exp_f32_e32 v64, v51
	v_sub_f32_e32 v51, v85, v77
	v_mul_f32_e32 v51, 0x3fb8aa3b, v51
	v_exp_f32_e32 v98, v51
	v_sub_f32_e32 v51, v85, v78
	v_mul_f32_e32 v51, 0x3fb8aa3b, v51
	v_exp_f32_e32 v65, v51
	v_sub_f32_e32 v51, v85, v79
	v_mul_f32_e32 v51, 0x3fb8aa3b, v51
	v_exp_f32_e32 v99, v51
	v_sub_f32_e32 v51, v85, v80
	v_mul_f32_e32 v51, 0x3fb8aa3b, v51
	v_exp_f32_e32 v100, v51
	v_sub_f32_e32 v51, v85, v81
	v_mul_f32_e32 v51, 0x3fb8aa3b, v51
	v_exp_f32_e32 v102, v51
	v_sub_f32_e32 v51, v85, v82
	v_mul_f32_e32 v51, 0x3fb8aa3b, v51
	v_exp_f32_e32 v101, v51
	v_mul_f32_e32 v51, 0x3fb8aa3b, v92
	v_exp_f32_e32 v103, v51
	v_sub_f32_e32 v51, v85, v83
	v_mul_f32_e32 v51, 0x3fb8aa3b, v51
	v_exp_f32_e32 v104, v51
	v_sub_f32_e32 v51, v85, v84
	v_mul_f32_e32 v51, 0x3fb8aa3b, v51
	v_exp_f32_e32 v106, v51
	v_sub_f32_e32 v51, v85, v86
	v_mul_f32_e32 v51, 0x3fb8aa3b, v51
	v_exp_f32_e32 v105, v51
	v_sub_f32_e32 v51, v85, v87
	v_mul_f32_e32 v51, 0x3fb8aa3b, v51
	v_exp_f32_e32 v107, v51
	v_sub_f32_e32 v51, v85, v88
	v_mul_f32_e32 v51, 0x3fb8aa3b, v51
	v_exp_f32_e32 v108, v51
	v_sub_f32_e32 v51, v85, v89
	v_mul_f32_e32 v51, 0x3fb8aa3b, v51
	v_exp_f32_e32 v110, v51
	v_sub_f32_e32 v51, v85, v90
	v_mul_f32_e32 v51, 0x3fb8aa3b, v51
	v_exp_f32_e32 v109, v51
	v_sub_f32_e32 v51, v85, v85
	v_mul_f32_e32 v51, 0x3fb8aa3b, v51
	v_pk_mul_f32 v[112:113], v[50:51], v[52:53] op_sel_hi:[0,1]
	v_pk_add_f32 v[52:53], v[54:55], 1.0 op_sel_hi:[1,0] neg_lo:[1,0] neg_hi:[1,0]
	v_exp_f32_e32 v111, v51
	v_pk_mul_f32 v[114:115], v[50:51], v[52:53] op_sel_hi:[0,1]
	v_pk_mul_f32 v[52:53], v[112:113], v[64:65]
	v_pk_mul_f32 v[64:65], v[50:51], v[56:57] op_sel_hi:[0,1]
	v_pk_add_f32 v[56:57], v[58:59], 1.0 op_sel_hi:[1,0] neg_lo:[1,0] neg_hi:[1,0]
	v_pk_mul_f32 v[54:55], v[114:115], v[98:99]
	v_pk_mul_f32 v[58:59], v[50:51], v[56:57] op_sel_hi:[0,1]
	v_pk_mul_f32 v[98:99], v[58:59], v[102:103]
	v_pk_mul_f32 v[56:57], v[64:65], v[100:101]
	v_bfe_u32 v51, v99, 16, 1
	v_bfe_u32 v100, v98, 16, 1
	v_bfe_u32 v101, v55, 16, 1
	v_bfe_u32 v102, v54, 16, 1
	v_add3_u32 v102, v54, v102, s73
	v_add3_u32 v101, v55, v101, s73
	v_add3_u32 v54, v98, v100, s73
	v_add3_u32 v51, v99, v51, s73
	v_bfe_u32 v55, v56, 16, 1
	v_bfe_u32 v98, v57, 16, 1
	v_bfe_u32 v99, v52, 16, 1
	v_bfe_u32 v100, v53, 16, 1
	v_add3_u32 v57, v57, v98, s73
	v_add3_u32 v55, v56, v55, s73
	v_add3_u32 v53, v53, v100, s73
	v_add3_u32 v52, v52, v99, s73
	v_lshrrev_b32_e32 v56, 16, v55
	v_lshrrev_b32_e32 v55, 16, v57
	v_lshrrev_b32_e32 v52, 16, v52
	v_lshrrev_b32_e32 v53, 16, v53
	v_and_or_b32 v55, v51, s26, v55
	v_and_or_b32 v54, v54, s26, v56
	v_and_or_b32 v53, v101, s26, v53
	v_and_or_b32 v52, v102, s26, v52
	ds_write_b128 v213, v[52:55] offset:4608
	v_pk_add_f32 v[52:53], v[60:61], 1.0 op_sel_hi:[1,0] neg_lo:[1,0] neg_hi:[1,0]
	s_nop 0
	v_pk_mul_f32 v[56:57], v[50:51], v[52:53] op_sel_hi:[0,1]
	v_pk_add_f32 v[52:53], v[62:63], 1.0 op_sel_hi:[1,0] neg_lo:[1,0] neg_hi:[1,0]
	v_pk_mul_f32 v[60:61], v[56:57], v[104:105]
	v_pk_mul_f32 v[54:55], v[50:51], v[52:53] op_sel_hi:[0,1]
	v_pk_add_f32 v[52:53], v[66:67], 1.0 op_sel_hi:[1,0] neg_lo:[1,0] neg_hi:[1,0]
	v_pk_add_f32 v[66:67], v[96:97], 1.0 op_sel_hi:[1,0] neg_lo:[1,0] neg_hi:[1,0]
	v_pk_mul_f32 v[52:53], v[50:51], v[52:53] op_sel_hi:[0,1]
	v_pk_mul_f32 v[50:51], v[50:51], v[66:67] op_sel_hi:[0,1]
	v_pk_mul_f32 v[96:97], v[50:51], v[110:111]
	v_pk_mul_f32 v[62:63], v[54:55], v[106:107]
	v_bfe_u32 v100, v97, 16, 1
	v_add3_u32 v97, v97, v100, s73
	v_bfe_u32 v100, v60, 16, 1
	v_bfe_u32 v99, v62, 16, 1
	v_add3_u32 v60, v60, v100, s73
	v_pk_mul_f32 v[66:67], v[52:53], v[108:109]
	v_bfe_u32 v98, v63, 16, 1
	v_bfe_u32 v101, v96, 16, 1
	v_add3_u32 v62, v62, v99, s73
	v_lshrrev_b32_e32 v60, 16, v60
	v_add3_u32 v63, v63, v98, s73
	v_add3_u32 v96, v96, v101, s73
	v_bfe_u32 v98, v66, 16, 1
	v_bfe_u32 v99, v67, 16, 1
	v_bfe_u32 v101, v61, 16, 1
	v_and_or_b32 v60, v62, s26, v60
	v_mul_f32_e32 v62, 0xbfb8aa3b, v75
	v_add3_u32 v61, v61, v101, s73
	v_add3_u32 v67, v67, v99, s73
	v_add3_u32 v66, v66, v98, s73
	v_exp_f32_e32 v98, v62
	v_lshrrev_b32_e32 v66, 16, v66
	v_lshrrev_b32_e32 v67, 16, v67
	v_lshrrev_b32_e32 v61, 16, v61
	v_and_or_b32 v61, v63, s26, v61
	v_and_or_b32 v63, v97, s26, v67
	v_and_or_b32 v62, v96, s26, v66
	ds_write_b128 v213, v[60:63] offset:4624
	v_sub_f32_e32 v61, v76, v68
	v_add_f32_e32 v60, 1.0, v98
	v_min_f32_e32 v61, 0x42700000, v61
	v_rcp_f32_e32 v60, v60
	v_mul_f32_e32 v61, 0x3fb8aa3b, v61
	v_exp_f32_e32 v61, v61
	ds_write_b128 v213, v[42:45] offset:7680
	ds_write_b128 v213, v[46:49] offset:7696
	v_mul_f32_e32 v42, v60, v75
	v_lshlrev_b32_e32 v44, 16, v74
	v_mul_f32_e32 v42, v42, v61
	v_bfe_u32 v43, v42, 16, 1
	v_add3_u32 v42, v42, v43, s73
	v_sub_f32_e32 v43, v68, v76
	v_mul_f32_e32 v45, 0xbfb8aa3b, v44
	v_min_f32_e32 v43, 0x42700000, v43
	v_exp_f32_e32 v45, v45
	v_mul_f32_e32 v43, 0x3fb8aa3b, v43
	v_exp_f32_e32 v43, v43
	v_sub_f32_e32 v46, v77, v68
	v_add_f32_e32 v45, 1.0, v45
	v_min_f32_e32 v46, 0x42700000, v46
	v_rcp_f32_e32 v45, v45
	v_mul_f32_e32 v46, 0x3fb8aa3b, v46
	ds_write_b16_d16_hi v202, v42
	v_mul_f32_e32 v42, v112, v43
	v_exp_f32_e32 v46, v46
	v_bfe_u32 v43, v42, 16, 1
	v_add3_u32 v42, v42, v43, s73
	ds_write_b16_d16_hi v202, v42 offset:2304
	v_mul_f32_e32 v42, v45, v44
	v_mul_f32_e32 v42, v42, v46
	v_bfe_u32 v43, v42, 16, 1
	v_lshlrev_b32_e32 v44, 16, v73
	v_add3_u32 v42, v42, v43, s73
	v_sub_f32_e32 v43, v68, v77
	v_mul_f32_e32 v45, 0xbfb8aa3b, v44
	v_min_f32_e32 v43, 0x42700000, v43
	v_exp_f32_e32 v45, v45
; __device__ __forceinline__ unsigned f2bf(float f) { unsigned u = __builtin_bit_cast(unsigned, f); return (u + 0x7fffu + ((u >> 16) & 1u)) >> 16; }
; __device__ __forceinline__ float bf1(bf16 h) { return __uint_as_float(((unsigned)h) << 16); }
; __device__ __forceinline__ float siluf(float v) { return v * sigmf(v); }
; template <bool OUT> __device__ __forceinline__ void hgrn_item2(const PA& a, LAS unsigned char* lds, int layer, int bh, int c, int wave, int lane, const HRaw& raw) {
;     ...
;         if (OUT) {
; #pragma unroll
;             for (int t = 0; t < 16; ++t) {
;                 QT[t * 72 + lane] = (bf16)f2bf(siluf(bf1(qr[t])) * __expf(fminf(cum[t] - c7, 60.f)));
;                 KT[t * 72 + lane] = (bf16)f2bf(kk[t] * __expf(fminf(c7 - cum[t], 60.f)));
;             }
	v_mul_f32_e32 v43, 0x3fb8aa3b, v43
	v_exp_f32_e32 v43, v43
	v_sub_f32_e32 v46, v78, v68
	v_add_f32_e32 v45, 1.0, v45
	v_min_f32_e32 v46, 0x42700000, v46
	v_rcp_f32_e32 v45, v45
	v_mul_f32_e32 v46, 0x3fb8aa3b, v46
	ds_write_b16_d16_hi v202, v42 offset:144
	v_mul_f32_e32 v42, v114, v43
	v_exp_f32_e32 v46, v46
	v_bfe_u32 v43, v42, 16, 1
	v_add3_u32 v42, v42, v43, s73
	ds_write_b16_d16_hi v202, v42 offset:2448
	v_mul_f32_e32 v42, v45, v44
	v_mul_f32_e32 v42, v42, v46
	v_bfe_u32 v43, v42, 16, 1
	v_lshlrev_b32_e32 v44, 16, v72
	v_add3_u32 v42, v42, v43, s73
	v_sub_f32_e32 v43, v68, v78
	v_mul_f32_e32 v45, 0xbfb8aa3b, v44
	v_min_f32_e32 v43, 0x42700000, v43
	v_exp_f32_e32 v45, v45
	v_mul_f32_e32 v43, 0x3fb8aa3b, v43
	v_exp_f32_e32 v43, v43
	v_sub_f32_e32 v46, v79, v68
	v_add_f32_e32 v45, 1.0, v45
	v_min_f32_e32 v46, 0x42700000, v46
	v_rcp_f32_e32 v45, v45
	v_mul_f32_e32 v46, 0x3fb8aa3b, v46
	ds_write_b16_d16_hi v202, v42 offset:288
	v_mul_f32_e32 v42, v113, v43
	v_exp_f32_e32 v46, v46
	v_bfe_u32 v43, v42, 16, 1
	v_add3_u32 v42, v42, v43, s73
	ds_write_b16_d16_hi v202, v42 offset:2592
	v_mul_f32_e32 v42, v45, v44
	v_mul_f32_e32 v42, v42, v46
	v_bfe_u32 v43, v42, 16, 1
	v_lshlrev_b32_e32 v44, 16, v71
	v_add3_u32 v42, v42, v43, s73
	v_sub_f32_e32 v43, v68, v79
	v_mul_f32_e32 v45, 0xbfb8aa3b, v44
	v_min_f32_e32 v43, 0x42700000, v43
	v_exp_f32_e32 v45, v45
	v_mul_f32_e32 v43, 0x3fb8aa3b, v43
	v_exp_f32_e32 v43, v43
	v_sub_f32_e32 v46, v80, v68
	v_add_f32_e32 v45, 1.0, v45
	v_min_f32_e32 v46, 0x42700000, v46
	v_rcp_f32_e32 v45, v45
	v_mul_f32_e32 v46, 0x3fb8aa3b, v46
	ds_write_b16_d16_hi v202, v42 offset:432
	v_mul_f32_e32 v42, v115, v43
	v_exp_f32_e32 v46, v46
	v_bfe_u32 v43, v42, 16, 1
	v_add3_u32 v42, v42, v43, s73
	ds_write_b16_d16_hi v202, v42 offset:2736
	v_mul_f32_e32 v42, v45, v44
	v_mul_f32_e32 v42, v42, v46
	v_bfe_u32 v43, v42, 16, 1
	v_lshlrev_b32_e32 v44, 16, v70
	v_add3_u32 v42, v42, v43, s73
	v_sub_f32_e32 v43, v68, v80
	v_mul_f32_e32 v45, 0xbfb8aa3b, v44
	v_min_f32_e32 v43, 0x42700000, v43
	v_exp_f32_e32 v45, v45
	v_mul_f32_e32 v43, 0x3fb8aa3b, v43
	v_exp_f32_e32 v43, v43
	v_sub_f32_e32 v46, v81, v68
	v_add_f32_e32 v45, 1.0, v45
	v_min_f32_e32 v46, 0x42700000, v46
	v_rcp_f32_e32 v45, v45
	v_mul_f32_e32 v46, 0x3fb8aa3b, v46
	ds_write_b16_d16_hi v202, v42 offset:576
	v_mul_f32_e32 v42, v64, v43
	v_exp_f32_e32 v46, v46
	v_bfe_u32 v43, v42, 16, 1
	v_add3_u32 v42, v42, v43, s73
	ds_write_b16_d16_hi v202, v42 offset:2880
	v_mul_f32_e32 v42, v45, v44
	v_mul_f32_e32 v42, v42, v46
	v_bfe_u32 v43, v42, 16, 1
	v_lshlrev_b32_e32 v44, 16, v69
	v_add3_u32 v42, v42, v43, s73
	v_sub_f32_e32 v43, v68, v81
	v_mul_f32_e32 v45, 0xbfb8aa3b, v44
	v_min_f32_e32 v43, 0x42700000, v43
	v_exp_f32_e32 v45, v45
	v_mul_f32_e32 v43, 0x3fb8aa3b, v43
	v_exp_f32_e32 v43, v43
	v_sub_f32_e32 v46, v82, v68
	v_add_f32_e32 v45, 1.0, v45
	v_min_f32_e32 v46, 0x42700000, v46
	v_rcp_f32_e32 v45, v45
	v_mul_f32_e32 v46, 0x3fb8aa3b, v46
	ds_write_b16_d16_hi v202, v42 offset:720
	v_mul_f32_e32 v42, v58, v43
	v_exp_f32_e32 v46, v46
	v_bfe_u32 v43, v42, 16, 1
	v_add3_u32 v42, v42, v43, s73
	ds_write_b16_d16_hi v202, v42 offset:3024
	v_mul_f32_e32 v42, v45, v44
	v_mul_f32_e32 v42, v42, v46
	v_mul_f32_e32 v44, 0xbfb8aa3b, v41
	v_bfe_u32 v43, v42, 16, 1
	v_exp_f32_e32 v44, v44
	v_add3_u32 v42, v42, v43, s73
	v_sub_f32_e32 v43, v68, v82
	v_min_f32_e32 v43, 0x42700000, v43
	v_mul_f32_e32 v43, 0x3fb8aa3b, v43
	v_sub_f32_e32 v45, v68, v68
	v_exp_f32_e32 v43, v43
	v_add_f32_e32 v44, 1.0, v44
	v_min_f32_e32 v45, 0x42700000, v45
	v_rcp_f32_e32 v44, v44
	v_mul_f32_e32 v45, 0x3fb8aa3b, v45
	v_exp_f32_e32 v45, v45
	ds_write_b16_d16_hi v202, v42 offset:864
	v_mul_f32_e32 v42, v65, v43
	v_bfe_u32 v43, v42, 16, 1
	v_mul_f32_e32 v41, v44, v41
	v_add3_u32 v42, v42, v43, s73
	v_mul_f32_e32 v41, v41, v45
	ds_write_b16_d16_hi v202, v42 offset:3168
	v_bfe_u32 v42, v41, 16, 1
	v_add3_u32 v41, v41, v42, s73
	s_waitcnt lgkmcnt(14)
	v_lshlrev_b32_e32 v42, 16, v116
	v_mul_f32_e32 v43, 0xbfb8aa3b, v42
	v_exp_f32_e32 v43, v43
	ds_write_b16_d16_hi v202, v41 offset:1008
	v_mul_f32_e32 v41, v59, v45
	v_sub_f32_e32 v45, v83, v68
	v_add_f32_e32 v43, 1.0, v43
	v_min_f32_e32 v45, 0x42700000, v45
	v_rcp_f32_e32 v43, v43
	v_mul_f32_e32 v45, 0x3fb8aa3b, v45
	v_exp_f32_e32 v45, v45
	v_bfe_u32 v44, v41, 16, 1
	v_add3_u32 v41, v41, v44, s73
	ds_write_b16_d16_hi v202, v41 offset:3312
	v_mul_f32_e32 v41, v43, v42
	v_mul_f32_e32 v41, v41, v45
	v_bfe_u32 v42, v41, 16, 1
	v_lshlrev_b32_e32 v43, 16, v117
	v_add3_u32 v41, v41, v42, s73
	v_sub_f32_e32 v42, v68, v83
	v_mul_f32_e32 v44, 0xbfb8aa3b, v43
	v_min_f32_e32 v42, 0x42700000, v42
	v_exp_f32_e32 v44, v44
	v_mul_f32_e32 v42, 0x3fb8aa3b, v42
	v_exp_f32_e32 v42, v42
	v_sub_f32_e32 v45, v84, v68
	v_add_f32_e32 v44, 1.0, v44
	v_min_f32_e32 v45, 0x42700000, v45
	v_rcp_f32_e32 v44, v44
	v_mul_f32_e32 v45, 0x3fb8aa3b, v45
	ds_write_b16_d16_hi v202, v41 offset:1152
	v_mul_f32_e32 v41, v56, v42
	v_exp_f32_e32 v45, v45
	v_bfe_u32 v42, v41, 16, 1
	v_add3_u32 v41, v41, v42, s73
	ds_write_b16_d16_hi v202, v41 offset:3456
	v_mul_f32_e32 v41, v44, v43
	v_mul_f32_e32 v41, v41, v45
	v_bfe_u32 v42, v41, 16, 1
	v_lshlrev_b32_e32 v43, 16, v118
	v_add3_u32 v41, v41, v42, s73
	v_sub_f32_e32 v42, v68, v84
	v_mul_f32_e32 v44, 0xbfb8aa3b, v43
	v_min_f32_e32 v42, 0x42700000, v42
	v_exp_f32_e32 v44, v44
	v_mul_f32_e32 v42, 0x3fb8aa3b, v42
	v_exp_f32_e32 v42, v42
	v_sub_f32_e32 v45, v86, v68
	v_add_f32_e32 v44, 1.0, v44
	v_min_f32_e32 v45, 0x42700000, v45
	v_rcp_f32_e32 v44, v44
	v_mul_f32_e32 v45, 0x3fb8aa3b, v45
	ds_write_b16_d16_hi v202, v41 offset:1296
	v_mul_f32_e32 v41, v54, v42
	v_exp_f32_e32 v45, v45
; __device__ __forceinline__ unsigned f2bf(float f) { unsigned u = __builtin_bit_cast(unsigned, f); return (u + 0x7fffu + ((u >> 16) & 1u)) >> 16; }
; __device__ __forceinline__ float bf1(bf16 h) { return __uint_as_float(((unsigned)h) << 16); }
; __device__ __forceinline__ float siluf(float v) { return v * sigmf(v); }
; template <bool OUT> __device__ __forceinline__ void hgrn_item2(const PA& a, LAS unsigned char* lds, int layer, int bh, int c, int wave, int lane, const HRaw& raw) {
;     ...
;         if (OUT) {
; #pragma unroll
;             for (int t = 0; t < 16; ++t) {
;                 QT[t * 72 + lane] = (bf16)f2bf(siluf(bf1(qr[t])) * __expf(fminf(cum[t] - c7, 60.f)));
;                 KT[t * 72 + lane] = (bf16)f2bf(kk[t] * __expf(fminf(c7 - cum[t], 60.f)));
;             }
	v_bfe_u32 v42, v41, 16, 1
	v_add3_u32 v41, v41, v42, s73
	ds_write_b16_d16_hi v202, v41 offset:3600
	v_mul_f32_e32 v41, v44, v43
	v_mul_f32_e32 v41, v41, v45
	v_bfe_u32 v42, v41, 16, 1
	v_lshlrev_b32_e32 v43, 16, v119
	v_add3_u32 v41, v41, v42, s73
	v_sub_f32_e32 v42, v68, v86
	v_mul_f32_e32 v44, 0xbfb8aa3b, v43
	v_min_f32_e32 v42, 0x42700000, v42
	v_exp_f32_e32 v44, v44
	v_mul_f32_e32 v42, 0x3fb8aa3b, v42
	v_exp_f32_e32 v42, v42
	v_sub_f32_e32 v45, v87, v68
	v_add_f32_e32 v44, 1.0, v44
	v_min_f32_e32 v45, 0x42700000, v45
	v_rcp_f32_e32 v44, v44
	v_mul_f32_e32 v45, 0x3fb8aa3b, v45
	ds_write_b16_d16_hi v202, v41 offset:1440
	v_mul_f32_e32 v41, v57, v42
	v_exp_f32_e32 v45, v45
	v_bfe_u32 v42, v41, 16, 1
	v_add3_u32 v41, v41, v42, s73
	ds_write_b16_d16_hi v202, v41 offset:3744
	v_mul_f32_e32 v41, v44, v43
	v_mul_f32_e32 v41, v41, v45
	v_bfe_u32 v42, v41, 16, 1
	v_lshlrev_b32_e32 v43, 16, v95
	v_add3_u32 v41, v41, v42, s73
	v_sub_f32_e32 v42, v68, v87
	v_mul_f32_e32 v44, 0xbfb8aa3b, v43
	v_min_f32_e32 v42, 0x42700000, v42
	v_exp_f32_e32 v44, v44
	v_mul_f32_e32 v42, 0x3fb8aa3b, v42
	v_exp_f32_e32 v42, v42
	v_sub_f32_e32 v45, v88, v68
	v_add_f32_e32 v44, 1.0, v44
	v_min_f32_e32 v45, 0x42700000, v45
	v_rcp_f32_e32 v44, v44
	v_mul_f32_e32 v45, 0x3fb8aa3b, v45
	ds_write_b16_d16_hi v202, v41 offset:1584
	v_mul_f32_e32 v41, v55, v42
	v_exp_f32_e32 v45, v45
	v_bfe_u32 v42, v41, 16, 1
	v_add3_u32 v41, v41, v42, s73
	ds_write_b16_d16_hi v202, v41 offset:3888
	v_mul_f32_e32 v41, v44, v43
	v_mul_f32_e32 v41, v41, v45
	v_bfe_u32 v42, v41, 16, 1
	v_lshlrev_b32_e32 v43, 16, v94
	v_add3_u32 v41, v41, v42, s73
	v_sub_f32_e32 v42, v68, v88
	v_mul_f32_e32 v44, 0xbfb8aa3b, v43
	v_min_f32_e32 v42, 0x42700000, v42
	v_exp_f32_e32 v44, v44
	v_mul_f32_e32 v42, 0x3fb8aa3b, v42
	v_exp_f32_e32 v42, v42
	v_sub_f32_e32 v45, v89, v68
	v_add_f32_e32 v44, 1.0, v44
	v_min_f32_e32 v45, 0x42700000, v45
	v_rcp_f32_e32 v44, v44
	v_mul_f32_e32 v45, 0x3fb8aa3b, v45
	ds_write_b16_d16_hi v202, v41 offset:1728
	v_mul_f32_e32 v41, v52, v42
	v_exp_f32_e32 v45, v45
	v_bfe_u32 v42, v41, 16, 1
	v_add3_u32 v41, v41, v42, s73
	ds_write_b16_d16_hi v202, v41 offset:4032
	v_mul_f32_e32 v41, v44, v43
	v_mul_f32_e32 v41, v41, v45
	v_bfe_u32 v42, v41, 16, 1
	v_lshlrev_b32_e32 v43, 16, v93
	v_add3_u32 v41, v41, v42, s73
	v_sub_f32_e32 v42, v68, v89
	v_mul_f32_e32 v44, 0xbfb8aa3b, v43
	v_min_f32_e32 v42, 0x42700000, v42
	v_exp_f32_e32 v44, v44
	v_mul_f32_e32 v42, 0x3fb8aa3b, v42
	v_exp_f32_e32 v42, v42
	v_sub_f32_e32 v45, v90, v68
	v_add_f32_e32 v44, 1.0, v44
	v_min_f32_e32 v45, 0x42700000, v45
	v_rcp_f32_e32 v44, v44
	v_mul_f32_e32 v45, 0x3fb8aa3b, v45
	ds_write_b16_d16_hi v202, v41 offset:1872
	v_mul_f32_e32 v41, v50, v42
	v_exp_f32_e32 v45, v45
	v_bfe_u32 v42, v41, 16, 1
	v_add3_u32 v41, v41, v42, s73
	ds_write_b16_d16_hi v202, v41 offset:4176
	v_mul_f32_e32 v41, v44, v43
	v_mul_f32_e32 v41, v41, v45
	v_bfe_u32 v42, v41, 16, 1
	v_add3_u32 v41, v41, v42, s73
	v_sub_f32_e32 v42, v68, v90
	v_min_f32_e32 v42, 0x42700000, v42
	v_lshlrev_b32_e32 v43, 16, v91
	v_mul_f32_e32 v42, 0x3fb8aa3b, v42
	v_mul_f32_e32 v44, 0xbfb8aa3b, v43
	v_exp_f32_e32 v42, v42
	v_exp_f32_e32 v44, v44
	ds_write_b16_d16_hi v202, v41 offset:2016
	v_min_f32_e32 v45, 0x42700000, v92
	v_mul_f32_e32 v41, v53, v42
	v_add_f32_e32 v44, 1.0, v44
	v_bfe_u32 v42, v41, 16, 1
	v_rcp_f32_e32 v44, v44
	v_mul_f32_e32 v45, 0x3fb8aa3b, v45
	v_exp_f32_e32 v45, v45
	v_add3_u32 v41, v41, v42, s73
	v_sub_f32_e32 v42, v68, v85
	v_min_f32_e32 v42, 0x42700000, v42
	v_mul_f32_e32 v42, 0x3fb8aa3b, v42
	ds_write_b16_d16_hi v202, v41 offset:4320
	v_mul_f32_e32 v41, v44, v43
	v_exp_f32_e32 v42, v42
	v_mul_f32_e32 v41, v41, v45
	v_bfe_u32 v43, v41, 16, 1
	v_add3_u32 v41, v41, v43, s73
	ds_write_b16_d16_hi v202, v41 offset:2160
	v_mul_f32_e32 v41, v51, v42
	v_bfe_u32 v42, v41, 16, 1
	v_add3_u32 v41, v41, v42, s73
	ds_write_b16_d16_hi v202, v41 offset:4464
	s_waitcnt lgkmcnt(0)
; #define LAS __attribute__((address_space(3)))
; #define LDS_WAIT() asm volatile("s_waitcnt lgkmcnt(0)" ::: "memory")
; __device__ __forceinline__ unsigned f2bf(float f) { unsigned u = __builtin_bit_cast(unsigned, f); return (u + 0x7fffu + ((u >> 16) & 1u)) >> 16; }
; template <bool OUT> __device__ __forceinline__ void hgrn_item2(const PA& a, LAS unsigned char* lds, int layer, int bh, int c, int wave, int lane, const HRaw& raw) {
;     ...
;     LDS_WAIT();
;     bf16x8 vfr[4];
; #pragma unroll
;     for (int nt = 0; nt < 4; ++nt) vfr[nt] = (q < 2) ? *(const LAS bf16x8*)(VT + (16 * nt + l15) * 24 + q * 8) : zero8;
;     f32x4 U[4][4];
; #pragma unroll
;     for (int mt = 0; mt < 4; ++mt) { const bf16x8 afr = (q < 2) ? *(const LAS bf16x8*)(KHT + (16 * mt + l15) * 24 + q * 8) : zero8;
; #pragma unroll
;         for (int nt = 0; nt < 4; ++nt) U[mt][nt] = __builtin_amdgcn_mfma_f32_16x16x32_bf16(afr, vfr[nt], (f32x4){0.f, 0.f, 0.f, 0.f}, 0, 0, 0); }
;     f32x4 o[4]; bf16x8 qf[2];
;     if (OUT) {
;         LDS_WAIT();
;         { const int rr = lane >> 3, cc = (lane & 7) * 8; *(LAS v4u*)(GT + rr * 72 + cc) = raw.g[0]; *(LAS v4u*)(GT + (rr + 8) * 72 + cc) = raw.g[1]; }
;         f32x4 sc = {0.f, 0.f, 0.f, 0.f};
; #pragma unroll
;         for (int ks = 0; ks < 2; ++ks) {
;             const v2u qa = *(const LAS v2u*)(QT + l15 * 72 + 32 * ks + 4 * q), qb = *(const LAS v2u*)(QT + l15 * 72 + 32 * ks + 16 + 4 * q);
;             const v2u ka = *(const LAS v2u*)(KT + l15 * 72 + 32 * ks + 4 * q), kb = *(const LAS v2u*)(KT + l15 * 72 + 32 * ks + 16 + 4 * q);
;             qf[ks] = __builtin_bit_cast(bf16x8, (v4u){qa.x, qa.y, qb.x, qb.y});
;             const bf16x8 kf = __builtin_bit_cast(bf16x8, (v4u){ka.x, ka.y, kb.x, kb.y});
;             sc = __builtin_amdgcn_mfma_f32_16x16x32_bf16(qf[ks], kf, sc, 0, 0, 0);
;         }
; #pragma unroll
;         for (int j = 0; j < 4; ++j) { const int t = 4 * q + j; P[t * 24 + l15] = (bf16)f2bf((l15 <= t) ? sc[j] : 0.f); }
;         LDS_WAIT();
;         const bf16x8 pf = (q < 2) ? *(const LAS bf16x8*)(P + l15 * 24 + q * 8) : zero8;
; #pragma unroll
;         for (int nt = 0; nt < 4; ++nt) o[nt] = __builtin_amdgcn_mfma_f32_16x16x32_bf16(pf, vfr[nt], (f32x4){0.f, 0.f, 0.f, 0.f}, 0, 0, 0);
;     }
	v_mov_b32_e32 v41, 0
	v_mov_b32_e32 v42, 0
	v_mov_b32_e32 v43, 0
	s_and_saveexec_b64 s[0:1], s[38:39]
	ds_read_b128 v[40:43], v214 offset:7680
	s_or_b64 exec, exec, s[0:1]
	v_mov_b32_e32 v124, 0
	v_mov_b32_e32 v44, 0
	v_mov_b32_e32 v45, 0
	v_mov_b32_e32 v46, 0
	v_mov_b32_e32 v47, 0
	s_and_saveexec_b64 s[0:1], s[38:39]
	ds_read_b128 v[44:47], v215 offset:7680
	s_or_b64 exec, exec, s[0:1]
	v_mov_b32_e32 v125, 0
	v_mov_b32_e32 v126, 0
	v_mov_b32_e32 v127, 0
	s_and_saveexec_b64 s[0:1], s[38:39]
	ds_read_b128 v[124:127], v214 offset:9216
	s_or_b64 exec, exec, s[0:1]
	v_mov_b32_e32 v48, 0
	v_mov_b32_e32 v52, 0
	v_mov_b32_e32 v53, 0
	v_mov_b32_e32 v54, 0
	v_mov_b32_e32 v55, 0
	s_and_saveexec_b64 s[0:1], s[38:39]
	ds_read_b128 v[52:55], v216 offset:7680
	s_or_b64 exec, exec, s[0:1]
	v_mov_b32_e32 v49, 0
	v_mov_b32_e32 v50, 0
	v_mov_b32_e32 v51, 0
	s_and_saveexec_b64 s[0:1], s[38:39]
	ds_read_b128 v[48:51], v214 offset:4608
	s_or_b64 exec, exec, s[0:1]
	s_waitcnt lgkmcnt(0)
	v_mfma_f32_16x16x32_bf16 v[56:59], v[48:51], v[40:43], 0
	v_mov_b32_e32 v84, 0
	v_mov_b32_e32 v85, 0
	v_mov_b32_e32 v86, 0
	v_mfma_f32_16x16x32_bf16 v[60:63], v[48:51], v[44:47], 0
	v_mov_b32_e32 v87, 0
	v_mfma_f32_16x16x32_bf16 v[64:67], v[48:51], v[124:127], 0
	v_mfma_f32_16x16x32_bf16 v[68:71], v[48:51], v[52:55], 0
	v_mov_b32_e32 v48, 0
	s_and_saveexec_b64 s[0:1], s[38:39]
	ds_read_b128 v[84:87], v215 offset:4608
	s_or_b64 exec, exec, s[0:1]
	s_waitcnt lgkmcnt(0)
	v_mfma_f32_16x16x32_bf16 v[72:75], v[84:87], v[40:43], 0
	v_mov_b32_e32 v49, 0
	v_mov_b32_e32 v50, 0
	v_mov_b32_e32 v51, 0
	v_mfma_f32_16x16x32_bf16 v[76:79], v[84:87], v[44:47], 0
	v_mfma_f32_16x16x32_bf16 v[80:83], v[84:87], v[124:127], 0
	v_mfma_f32_16x16x32_bf16 v[84:87], v[84:87], v[52:55], 0
	s_and_saveexec_b64 s[0:1], s[38:39]
	ds_read_b128 v[48:51], v214 offset:6144
	s_or_b64 exec, exec, s[0:1]
	s_waitcnt lgkmcnt(0)
	v_mfma_f32_16x16x32_bf16 v[88:91], v[48:51], v[40:43], 0
	v_mov_b32_e32 v104, 0
	v_mov_b32_e32 v120, 0
	v_mov_b32_e32 v121, 0
	v_mfma_f32_16x16x32_bf16 v[92:95], v[48:51], v[44:47], 0
	v_mov_b32_e32 v122, 0
	v_mov_b32_e32 v123, 0
	v_mfma_f32_16x16x32_bf16 v[96:99], v[48:51], v[124:127], 0
	v_mfma_f32_16x16x32_bf16 v[100:103], v[48:51], v[52:55], 0
	s_and_saveexec_b64 s[0:1], s[38:39]
	ds_read_b128 v[120:123], v216 offset:4608
	s_or_b64 exec, exec, s[0:1]
	s_waitcnt lgkmcnt(0)
	ds_write_b128 v204, v[32:35] offset:4608
	s_waitcnt vmcnt(8)
	ds_write_b128 v204, v[36:39] offset:5760
	ds_read2_b64 v[48:51], v205 offset1:4
	v_add_u32_e32 v236, 0x800, v205
	ds_read2_b64 v[36:39], v236 offset0:32 offset1:36
	ds_read2_b64 v[32:35], v205 offset0:8 offset1:12
	ds_read2_b64 v[116:119], v236 offset0:40 offset1:44
	s_waitcnt lgkmcnt(6)
	v_mfma_f32_16x16x32_bf16 v[108:111], v[120:123], v[40:43], 0
	s_mov_b32 s13, 0
	v_mov_b32_e32 v107, 0
	s_waitcnt lgkmcnt(2)
	v_mfma_f32_16x16x32_bf16 v[36:39], v[48:51], v[36:39], 0
	s_waitcnt lgkmcnt(0)
	v_mfma_f32_16x16x32_bf16 v[36:39], v[32:35], v[116:119], v[36:39]
	v_mfma_f32_16x16x32_bf16 v[112:115], v[120:123], v[44:47], 0
	v_mfma_f32_16x16x32_bf16 v[116:119], v[120:123], v[124:127], 0
	s_nop 5
	v_cndmask_b32_e64 v36, v36, 0, s[40:41]
	v_cndmask_b32_e64 v37, v37, 0, s[42:43]
	v_bfe_u32 v105, v36, 16, 1
	v_cndmask_b32_e64 v38, v38, 0, s[44:45]
	v_bfe_u32 v106, v37, 16, 1
	v_add3_u32 v36, v36, v105, s73
	v_add3_u32 v37, v37, v106, s73
	ds_write_b16_d16_hi v217, v36 offset:10752
	ds_write_b16_d16_hi v217, v37 offset:10800
	v_bfe_u32 v36, v38, 16, 1
	v_add3_u32 v36, v38, v36, s73
	ds_write_b16_d16_hi v217, v36 offset:10848
	v_cndmask_b32_e64 v36, v39, 0, s[46:47]
	v_bfe_u32 v37, v36, 16, 1
	v_add3_u32 v36, v36, v37, s73
	v_mfma_f32_16x16x32_bf16 v[120:123], v[120:123], v[52:55], 0
	ds_write_b16_d16_hi v218, v36 offset:10752
	s_waitcnt lgkmcnt(0)
	v_mov_b32_e32 v105, 0
	v_mov_b32_e32 v106, 0
	s_and_saveexec_b64 s[0:1], s[38:39]
	ds_read_b128 v[104:107], v219 offset:10752
	s_or_b64 exec, exec, s[0:1]
	s_lshl_b32 s11, s11, 6
	s_or_b32 s0, s11, s12
	s_ashr_i32 s1, s0, 31
	s_lshl_b64 s[0:1], s[0:1], 14
	s_add_u32 s0, s89, s0
	s_addc_u32 s1, s25, s1
	s_waitcnt lgkmcnt(0)
	v_mfma_f32_16x16x32_bf16 v[40:43], v[104:107], v[40:43], 0
	s_add_i32 s0, 0, 0x18000
	v_add_u32_e32 v222, s0, v206
	v_add_u32_e32 v223, s0, v207
	v_mfma_f32_16x16x32_bf16 v[36:39], v[104:107], v[124:127], 0
	s_waitcnt vmcnt(0)
	s_waitcnt lgkmcnt(0)
	s_barrier
	s_branch .LBB0_730

; #define LAS __attribute__((address_space(3)))
; __device__ __forceinline__ unsigned pk2(float lo, float hi) { return f2bf(lo) | (f2bf(hi) << 16); }
; template <bool OUT> __device__ __forceinline__ void hgrn_item2(const PA& a, LAS unsigned char* lds, int layer, int bh, int c, int wave, int lane, const HRaw& raw) {
;     ...
;     if (OUT) {
; #pragma unroll
;         for (int mt = 0; mt < 4; ++mt) { const f32x4 Ev = *(const LAS f32x4*)(E7L + 16 * mt + 4 * q);
; #pragma unroll
;             for (int nt = 0; nt < 4; ++nt) Sp[mt][nt] = Sp[mt][nt] * Ev; }
; #pragma unroll
;         for (int nt = 0; nt < 4; ++nt)
; #pragma unroll
;             for (int ks = 0; ks < 2; ++ks) {
;                 const f32x4 s0 = Sp[2 * ks][nt], s1 = Sp[2 * ks + 1][nt];
;                 const bf16x8 bfrag = __builtin_bit_cast(bf16x8, (v4u){pk2(s0[0], s0[1]), pk2(s0[2], s0[3]), pk2(s1[0], s1[1]), pk2(s1[2], s1[3])});
;                 o[nt] = __builtin_amdgcn_mfma_f32_16x16x32_bf16(qf[ks], bfrag, o[nt], 0, 0, 0);
;             }
.LBB0_732:
	v_add_u32_e32 v251, s3, v208
	ds_read_b128 v[64:67], v251 offset:11776
	ds_read_b128 v[80:83], v251 offset:11904
	v_mfma_f32_16x16x32_bf16 v[44:47], v[104:107], v[44:47], 0
	v_readlane_b32 s0, v253, 29
	v_readlane_b32 s1, v253, 30
	s_waitcnt lgkmcnt(1)
	v_pk_mul_f32 v[84:85], v[138:139], v[66:67]
	v_pk_mul_f32 v[72:73], v[154:155], v[66:67]
	v_pk_mul_f32 v[60:61], v[170:171], v[66:67]
	v_pk_mul_f32 v[56:57], v[182:183], v[66:67]
	ds_read_b128 v[66:69], v251 offset:11840
	v_mfma_f32_16x16x32_bf16 v[52:55], v[104:107], v[52:55], 0
	v_mul_f32_e64 v86, v136, v64
	v_mul_f32_e64 v87, v137, v65
	v_pk_mul_f32 v[74:75], v[152:153], v[64:65]
	v_pk_mul_f32 v[62:63], v[168:169], v[64:65]
	v_pk_mul_f32 v[58:59], v[180:181], v[64:65]
	s_waitcnt lgkmcnt(0)
	v_pk_mul_f32 v[88:89], v[134:135], v[68:69]
	v_pk_mul_f32 v[92:93], v[126:127], v[68:69]
	v_pk_mul_f32 v[76:77], v[146:147], v[68:69]
	v_pk_mul_f32 v[64:65], v[162:163], v[68:69]
	v_pk_mul_f32 v[96:97], v[158:159], v[82:83]
	v_pk_mul_f32 v[98:99], v[156:157], v[80:81]
	v_pk_mul_f32 v[100:101], v[174:175], v[82:83]
	v_pk_mul_f32 v[102:103], v[172:173], v[80:81]
	v_pk_mul_f32 v[104:105], v[178:179], v[82:83]
	v_pk_mul_f32 v[106:107], v[176:177], v[80:81]
	v_pk_mul_f32 v[68:69], v[186:187], v[82:83]
	v_pk_mul_f32 v[70:71], v[184:185], v[80:81]
	ds_read_b128 v[80:83], v251 offset:11968
	v_pk_mul_f32 v[90:91], v[132:133], v[66:67]
	v_pk_mul_f32 v[94:95], v[124:125], v[66:67]
	v_pk_mul_f32 v[78:79], v[144:145], v[66:67]
	v_pk_mul_f32 v[66:67], v[160:161], v[66:67]
	s_waitcnt lgkmcnt(0)
	v_pk_mul_f32 v[110:111], v[140:141], v[80:81]
	v_pk_mul_f32 v[114:115], v[128:129], v[80:81]
	v_pk_mul_f32 v[118:119], v[148:149], v[80:81]
	v_pk_mul_f32 v[122:123], v[164:165], v[80:81]
	v_bfe_u32 v80, v86, 16, 1
	v_add3_u32 v80, v86, v80, s73
	v_bfe_u32 v81, v87, 16, 1
	v_lshrrev_b32_e32 v80, 16, v80
	v_add3_u32 v81, v87, v81, s73
	v_and_or_b32 v80, v81, s26, v80
	v_bfe_u32 v81, v84, 16, 1
	v_pk_mul_f32 v[108:109], v[142:143], v[82:83]
	v_pk_mul_f32 v[112:113], v[130:131], v[82:83]
	v_pk_mul_f32 v[116:117], v[150:151], v[82:83]
	v_pk_mul_f32 v[120:121], v[166:167], v[82:83]
	v_add3_u32 v81, v84, v81, s73
	v_bfe_u32 v82, v85, 16, 1
	v_lshrrev_b32_e32 v81, 16, v81
	v_add3_u32 v82, v85, v82, s73
	v_and_or_b32 v81, v82, s26, v81
	v_bfe_u32 v82, v90, 16, 1
	v_add3_u32 v82, v90, v82, s73
	v_bfe_u32 v83, v91, 16, 1
	v_lshrrev_b32_e32 v82, 16, v82
	v_add3_u32 v83, v91, v83, s73
	v_and_or_b32 v82, v83, s26, v82
	v_bfe_u32 v83, v88, 16, 1
	v_add3_u32 v83, v88, v83, s73
	v_bfe_u32 v84, v89, 16, 1
	v_lshrrev_b32_e32 v83, 16, v83
	v_add3_u32 v84, v89, v84, s73
	v_and_or_b32 v83, v84, s26, v83
	v_bfe_u32 v84, v109, 16, 1
	v_add3_u32 v84, v109, v84, s73
	v_mfma_f32_16x16x32_bf16 v[40:43], v[48:51], v[80:83], v[40:43]
	v_bfe_u32 v80, v98, 16, 1
	v_add3_u32 v80, v98, v80, s73
	v_bfe_u32 v81, v99, 16, 1
	v_lshrrev_b32_e32 v80, 16, v80
	v_add3_u32 v81, v99, v81, s73
	v_and_or_b32 v80, v81, s26, v80
	v_bfe_u32 v81, v96, 16, 1
	v_add3_u32 v81, v96, v81, s73
	v_bfe_u32 v82, v97, 16, 1
	v_lshrrev_b32_e32 v81, 16, v81
	v_add3_u32 v82, v97, v82, s73
	v_and_or_b32 v81, v82, s26, v81
	v_bfe_u32 v82, v110, 16, 1
	v_add3_u32 v82, v110, v82, s73
	v_bfe_u32 v83, v111, 16, 1
	v_lshrrev_b32_e32 v82, 16, v82
	v_add3_u32 v83, v111, v83, s73
	v_and_or_b32 v82, v83, s26, v82
	v_bfe_u32 v83, v108, 16, 1
	v_add3_u32 v83, v108, v83, s73
	v_lshrrev_b32_e32 v83, 16, v83
	v_and_or_b32 v83, v84, s26, v83
	s_lshl_b32 s62, s10, 7
	s_lshl_b32 s12, s10, 6
	v_mfma_f32_16x16x32_bf16 v[40:43], v[32:35], v[80:83], v[40:43]
	v_bfe_u32 v80, v74, 16, 1
	v_add3_u32 v74, v74, v80, s73
	v_bfe_u32 v80, v75, 16, 1
	v_lshrrev_b32_e32 v74, 16, v74
	v_add3_u32 v75, v75, v80, s73
	v_and_or_b32 v80, v75, s26, v74
	v_bfe_u32 v74, v72, 16, 1
	v_add3_u32 v72, v72, v74, s73
	v_bfe_u32 v74, v73, 16, 1
	v_lshrrev_b32_e32 v72, 16, v72
	v_add3_u32 v73, v73, v74, s73
	v_and_or_b32 v81, v73, s26, v72
	v_bfe_u32 v72, v94, 16, 1
	v_add3_u32 v72, v94, v72, s73
	v_bfe_u32 v73, v95, 16, 1
	v_lshrrev_b32_e32 v72, 16, v72
	v_add3_u32 v73, v95, v73, s73
	v_and_or_b32 v82, v73, s26, v72
	v_bfe_u32 v72, v92, 16, 1
	v_add3_u32 v72, v92, v72, s73
	v_bfe_u32 v73, v93, 16, 1
	v_lshrrev_b32_e32 v72, 16, v72
	v_add3_u32 v73, v93, v73, s73
	v_and_or_b32 v83, v73, s26, v72
	v_bfe_u32 v72, v102, 16, 1
	v_add3_u32 v72, v102, v72, s73
	v_bfe_u32 v73, v103, 16, 1
	v_lshrrev_b32_e32 v72, 16, v72
	v_add3_u32 v73, v103, v73, s73
	v_and_or_b32 v72, v73, s26, v72
	v_bfe_u32 v73, v100, 16, 1
	v_add3_u32 v73, v100, v73, s73
	v_bfe_u32 v74, v101, 16, 1
	v_lshrrev_b32_e32 v73, 16, v73
	v_add3_u32 v74, v101, v74, s73
	v_and_or_b32 v73, v74, s26, v73
	v_bfe_u32 v74, v114, 16, 1
	v_add3_u32 v74, v114, v74, s73
	v_bfe_u32 v75, v115, 16, 1
	v_lshrrev_b32_e32 v74, 16, v74
	v_add3_u32 v75, v115, v75, s73
	v_mfma_f32_16x16x32_bf16 v[44:47], v[48:51], v[80:83], v[44:47]
	v_and_or_b32 v74, v75, s26, v74
	v_bfe_u32 v75, v112, 16, 1
	v_add3_u32 v75, v112, v75, s73
	v_bfe_u32 v80, v113, 16, 1
	v_lshrrev_b32_e32 v75, 16, v75
	v_add3_u32 v80, v113, v80, s73
	v_and_or_b32 v75, v80, s26, v75
	s_nop 1
	v_mfma_f32_16x16x32_bf16 v[44:47], v[32:35], v[72:75], v[44:47]
	v_bfe_u32 v72, v62, 16, 1
	v_add3_u32 v62, v62, v72, s73
	v_bfe_u32 v72, v63, 16, 1
	v_lshrrev_b32_e32 v62, 16, v62
	v_add3_u32 v63, v63, v72, s73
	v_and_or_b32 v72, v63, s26, v62
	v_bfe_u32 v62, v60, 16, 1
	v_add3_u32 v60, v60, v62, s73
	v_bfe_u32 v62, v61, 16, 1
	v_lshrrev_b32_e32 v60, 16, v60
	v_add3_u32 v61, v61, v62, s73
	v_and_or_b32 v73, v61, s26, v60
	v_bfe_u32 v60, v78, 16, 1
	v_add3_u32 v60, v78, v60, s73
	v_bfe_u32 v61, v79, 16, 1
	v_lshrrev_b32_e32 v60, 16, v60
; __device__ __forceinline__ unsigned f2bf(float f) { unsigned u = __builtin_bit_cast(unsigned, f); return (u + 0x7fffu + ((u >> 16) & 1u)) >> 16; }
; __device__ __forceinline__ unsigned pk2(float lo, float hi) { return f2bf(lo) | (f2bf(hi) << 16); }
; __device__ __forceinline__ float bf1(bf16 h) { return __uint_as_float(((unsigned)h) << 16); }
; __device__ __forceinline__ float siluf(float v) { return v * sigmf(v); }
; template <bool OUT> __device__ __forceinline__ void hgrn_item2(const PA& a, LAS unsigned char* lds, int layer, int bh, int c, int wave, int lane, const HRaw& raw) {
;     ...
;         for (int nt = 0; nt < 4; ++nt)
; #pragma unroll
;             for (int ks = 0; ks < 2; ++ks) {
;                 const f32x4 s0 = Sp[2 * ks][nt], s1 = Sp[2 * ks + 1][nt];
;                 const bf16x8 bfrag = __builtin_bit_cast(bf16x8, (v4u){pk2(s0[0], s0[1]), pk2(s0[2], s0[3]), pk2(s1[0], s1[1]), pk2(s1[2], s1[3])});
;                 o[nt] = __builtin_amdgcn_mfma_f32_16x16x32_bf16(qf[ks], bfrag, o[nt], 0, 0, 0);
;             }
;         float gn[4];
; #pragma unroll
;         for (int nt = 0; nt < 4; ++nt) gn[nt] = a.in[5][layer * 64 + 16 * nt + l15];
; #pragma unroll
;         for (int j = 0; j < 4; ++j) {
;             float ss = (o[0][j] * o[0][j] + o[1][j] * o[1][j]) + (o[2][j] * o[2][j] + o[3][j] * o[3][j]);
;             ss += __shfl_xor(ss, 1); ss += __shfl_xor(ss, 2); ss += __shfl_xor(ss, 4); ss += __shfl_xor(ss, 8);
;             const float rs = __builtin_amdgcn_rsqf(ss * (1.f / 64.f) + EPS);
; #pragma unroll
;             for (int nt = 0; nt < 4; ++nt) { const float gt = siluf(bf1(GT[(4 * q + j) * 72 + 16 * nt + l15]));
;                 OT[(4 * q + j) * 72 + 16 * nt + l15] = (bf16)f2bf(o[nt][j] * rs * gn[nt] * gt); }
;         }
	v_add3_u32 v61, v79, v61, s73
	v_and_or_b32 v74, v61, s26, v60
	v_bfe_u32 v60, v76, 16, 1
	v_add3_u32 v60, v76, v60, s73
	v_bfe_u32 v61, v77, 16, 1
	v_lshrrev_b32_e32 v60, 16, v60
	v_add3_u32 v61, v77, v61, s73
	v_and_or_b32 v75, v61, s26, v60
	v_bfe_u32 v60, v106, 16, 1
	v_add3_u32 v60, v106, v60, s73
	v_bfe_u32 v61, v107, 16, 1
	v_lshrrev_b32_e32 v60, 16, v60
	v_add3_u32 v61, v107, v61, s73
	v_and_or_b32 v60, v61, s26, v60
	v_bfe_u32 v61, v104, 16, 1
	v_add3_u32 v61, v104, v61, s73
	v_bfe_u32 v62, v105, 16, 1
	v_lshrrev_b32_e32 v61, 16, v61
	v_add3_u32 v62, v105, v62, s73
	v_and_or_b32 v61, v62, s26, v61
	v_bfe_u32 v62, v118, 16, 1
	v_add3_u32 v62, v118, v62, s73
	v_bfe_u32 v63, v119, 16, 1
	v_lshrrev_b32_e32 v62, 16, v62
	v_add3_u32 v63, v119, v63, s73
	v_mfma_f32_16x16x32_bf16 v[36:39], v[48:51], v[72:75], v[36:39]
	v_and_or_b32 v62, v63, s26, v62
	v_bfe_u32 v63, v116, 16, 1
	v_add3_u32 v63, v116, v63, s73
	v_bfe_u32 v72, v117, 16, 1
	v_lshrrev_b32_e32 v63, 16, v63
	v_add3_u32 v72, v117, v72, s73
	v_and_or_b32 v63, v72, s26, v63
	s_nop 1
	v_mfma_f32_16x16x32_bf16 v[36:39], v[32:35], v[60:63], v[36:39]
	v_bfe_u32 v60, v58, 16, 1
	v_add3_u32 v58, v58, v60, s73
	v_bfe_u32 v60, v59, 16, 1
	v_lshrrev_b32_e32 v58, 16, v58
	v_add3_u32 v59, v59, v60, s73
	v_and_or_b32 v58, v59, s26, v58
	v_bfe_u32 v59, v56, 16, 1
	v_add3_u32 v56, v56, v59, s73
	v_bfe_u32 v59, v57, 16, 1
	v_lshrrev_b32_e32 v56, 16, v56
	v_add3_u32 v57, v57, v59, s73
	v_and_or_b32 v59, v57, s26, v56
	v_bfe_u32 v56, v66, 16, 1
	v_add3_u32 v56, v66, v56, s73
	v_bfe_u32 v57, v67, 16, 1
	v_lshrrev_b32_e32 v56, 16, v56
	v_add3_u32 v57, v67, v57, s73
	v_and_or_b32 v60, v57, s26, v56
	v_bfe_u32 v56, v64, 16, 1
	v_add3_u32 v56, v64, v56, s73
	v_bfe_u32 v57, v65, 16, 1
	v_lshrrev_b32_e32 v56, 16, v56
	v_add3_u32 v57, v65, v57, s73
	v_and_or_b32 v61, v57, s26, v56
	v_bfe_u32 v56, v121, 16, 1
	v_add3_u32 v56, v121, v56, s73
	v_mfma_f32_16x16x32_bf16 v[48:51], v[48:51], v[58:61], v[52:55]
	s_nop 2
	v_bfe_u32 v52, v70, 16, 1
	v_add3_u32 v52, v70, v52, s73
	v_bfe_u32 v53, v71, 16, 1
	v_lshrrev_b32_e32 v52, 16, v52
	v_add3_u32 v53, v71, v53, s73
	v_and_or_b32 v52, v53, s26, v52
	v_bfe_u32 v53, v68, 16, 1
	v_add3_u32 v53, v68, v53, s73
	v_bfe_u32 v54, v69, 16, 1
	v_lshrrev_b32_e32 v53, 16, v53
	v_add3_u32 v54, v69, v54, s73
	v_and_or_b32 v53, v54, s26, v53
	v_bfe_u32 v54, v122, 16, 1
	v_add3_u32 v54, v122, v54, s73
	v_bfe_u32 v55, v123, 16, 1
	v_lshrrev_b32_e32 v54, 16, v54
	v_add3_u32 v55, v123, v55, s73
	v_and_or_b32 v54, v55, s26, v54
	v_bfe_u32 v55, v120, 16, 1
	v_add3_u32 v55, v120, v55, s73
	v_lshrrev_b32_e32 v55, 16, v55
	v_and_or_b32 v55, v56, s26, v55
	s_nop 1
	v_mfma_f32_16x16x32_bf16 v[32:35], v[32:35], v[52:55], v[48:51]
	s_nop 2
	v_lshlrev_b32_e32 v48, 5, v234
	v_add_u32_e32 v48, 0x1e000, v48
	ds_read_b128 v[48:51], v48
	s_nop 3
	v_and_b32_e32 v53, 64, v237
	v_xor_b32_e32 v52, 1, v237
	v_add_u32_e32 v53, 64, v53
	v_cmp_lt_i32_e32 vcc, v52, v53
	s_nop 1
	v_cndmask_b32_e32 v52, v237, v52, vcc
	v_lshlrev_b32_e32 v159, 2, v52
	v_xor_b32_e32 v52, 2, v237
	v_cmp_lt_i32_e32 vcc, v52, v53
	s_nop 1
	v_cndmask_b32_e32 v52, v237, v52, vcc
	v_lshlrev_b32_e32 v158, 2, v52
	v_xor_b32_e32 v52, 4, v237
	v_cmp_lt_i32_e32 vcc, v52, v53
	s_nop 1
	v_cndmask_b32_e32 v52, v237, v52, vcc
	v_lshlrev_b32_e32 v156, 2, v52
	v_xor_b32_e32 v52, 8, v237
	v_cmp_lt_i32_e32 vcc, v52, v53
	v_mul_f32_e32 v53, v32, v32
	v_fmac_f32_e32 v53, v36, v36
	v_cndmask_b32_e32 v52, v237, v52, vcc
	v_lshlrev_b32_e32 v157, 2, v52
	v_mul_f32_e32 v52, v44, v44
	v_fmac_f32_e32 v52, v40, v40
	v_add_f32_e32 v52, v52, v53
	ds_bpermute_b32 v53, v159, v52
	s_waitcnt lgkmcnt(0)
	v_add_f32_e32 v52, v52, v53
	ds_bpermute_b32 v53, v158, v52
	s_waitcnt lgkmcnt(0)
	v_add_f32_e32 v52, v52, v53
	ds_bpermute_b32 v53, v156, v52
	s_waitcnt lgkmcnt(0)
	v_add_f32_e32 v52, v52, v53
	ds_bpermute_b32 v53, v157, v52
	s_waitcnt lgkmcnt(0)
	v_add_f32_e32 v52, v52, v53
	ds_read_u16 v53, v209 offset:4608
	ds_read_u16 v54, v209 offset:4640
	v_fmamk_f32 v52, v52, 0x3c800000, v235
	v_rsq_f32_e32 v52, v52
	s_waitcnt lgkmcnt(0)
	v_lshlrev_b32_e32 v53, 16, v53
	v_mul_f32_e32 v55, 0xbfb8aa3b, v53
	v_exp_f32_e32 v55, v55
	v_mul_f32_e32 v40, v40, v52
	v_mul_f32_e32 v44, v44, v52
	v_mul_f32_e32 v36, v36, v52
	v_add_f32_e32 v55, 1.0, v55
	v_rcp_f32_e32 v55, v55
	v_mul_f32_e32 v32, v32, v52
	v_mul_f32_e32 v53, v55, v53
	s_waitcnt vmcnt(0) lgkmcnt(0)
	v_readfirstlane_b32 s98, v206
	s_add_i32 m0, s98, 0x18000
	s_or_b32 s98, s11, s9
	s_ashr_i32 s99, s98, 31
	s_lshl_b64 s[98:99], s[98:99], 14
	s_add_u32 s98, s89, s98
	s_addc_u32 s99, s25, s99
	global_load_lds_dwordx4 v224, s[98:99]
	s_add_i32 m0, m0, 0x400
	s_nop 0
	global_load_lds_dwordx4 v240, s[98:99]
	v_mul_f32_e32 v40, v50, v40
	v_mul_f32_e32 v40, v40, v53
	v_bfe_u32 v53, v40, 16, 1
	v_add3_u32 v40, v40, v53, s73
	ds_write_b16_d16_hi v209, v40 offset:7680
	v_lshlrev_b32_e32 v40, 16, v54
	v_mul_f32_e32 v53, 0xbfb8aa3b, v40
	v_exp_f32_e32 v53, v53
	v_mul_f32_e32 v44, v51, v44
	v_mul_f32_e32 v36, v49, v36
	v_mul_f32_e32 v32, v48, v32
	v_add_f32_e32 v53, 1.0, v53
	v_rcp_f32_e32 v53, v53
	s_nop 0
	v_mul_f32_e32 v40, v53, v40
	v_mul_f32_e32 v40, v44, v40
	v_bfe_u32 v44, v40, 16, 1
	v_add3_u32 v40, v40, v44, s73
	ds_write_b16_d16_hi v209, v40 offset:7712
	ds_read_u16 v40, v209 offset:4672
	s_waitcnt lgkmcnt(0)
	v_lshlrev_b32_e32 v40, 16, v40
	v_mul_f32_e32 v44, 0xbfb8aa3b, v40
	v_exp_f32_e32 v44, v44
	s_nop 0
	v_add_f32_e32 v44, 1.0, v44
	v_rcp_f32_e32 v44, v44
	s_nop 0
	v_mul_f32_e32 v40, v44, v40
	v_mul_f32_e32 v36, v36, v40
	v_bfe_u32 v40, v36, 16, 1
	v_add3_u32 v36, v36, v40, s73
	ds_write_b16_d16_hi v209, v36 offset:7744
	ds_read_u16 v36, v209 offset:4704
	s_waitcnt lgkmcnt(0)
; __device__ __forceinline__ unsigned f2bf(float f) { unsigned u = __builtin_bit_cast(unsigned, f); return (u + 0x7fffu + ((u >> 16) & 1u)) >> 16; }
; __device__ __forceinline__ float bf1(bf16 h) { return __uint_as_float(((unsigned)h) << 16); }
; __device__ __forceinline__ float siluf(float v) { return v * sigmf(v); }
; template <bool OUT> __device__ __forceinline__ void hgrn_item2(const PA& a, LAS unsigned char* lds, int layer, int bh, int c, int wave, int lane, const HRaw& raw) {
;     ...
; #pragma unroll
;         for (int j = 0; j < 4; ++j) {
;             float ss = (o[0][j] * o[0][j] + o[1][j] * o[1][j]) + (o[2][j] * o[2][j] + o[3][j] * o[3][j]);
;             ss += __shfl_xor(ss, 1); ss += __shfl_xor(ss, 2); ss += __shfl_xor(ss, 4); ss += __shfl_xor(ss, 8);
;             const float rs = __builtin_amdgcn_rsqf(ss * (1.f / 64.f) + EPS);
; #pragma unroll
;             for (int nt = 0; nt < 4; ++nt) { const float gt = siluf(bf1(GT[(4 * q + j) * 72 + 16 * nt + l15]));
;                 OT[(4 * q + j) * 72 + 16 * nt + l15] = (bf16)f2bf(o[nt][j] * rs * gn[nt] * gt); }
;         }
	v_lshlrev_b32_e32 v36, 16, v36
	v_mul_f32_e32 v40, 0xbfb8aa3b, v36
	v_exp_f32_e32 v40, v40
	s_nop 0
	v_add_f32_e32 v40, 1.0, v40
	v_rcp_f32_e32 v40, v40
	s_nop 0
	v_mul_f32_e32 v36, v40, v36
	v_mul_f32_e32 v32, v32, v36
	v_bfe_u32 v36, v32, 16, 1
	v_add3_u32 v32, v32, v36, s73
	ds_write_b16_d16_hi v209, v32 offset:7776
	v_mul_f32_e32 v32, v45, v45
	v_mul_f32_e32 v36, v33, v33
	v_fmac_f32_e32 v32, v41, v41
	v_fmac_f32_e32 v36, v37, v37
	v_add_f32_e32 v32, v32, v36
	ds_bpermute_b32 v36, v159, v32
	s_waitcnt lgkmcnt(0)
	v_add_f32_e32 v32, v32, v36
	ds_bpermute_b32 v36, v158, v32
	s_waitcnt lgkmcnt(0)
	v_add_f32_e32 v32, v32, v36
	ds_bpermute_b32 v36, v156, v32
	s_waitcnt lgkmcnt(0)
	v_add_f32_e32 v32, v32, v36
	ds_bpermute_b32 v36, v157, v32
	s_waitcnt lgkmcnt(0)
	v_add_f32_e32 v32, v32, v36
	ds_read_u16 v36, v210 offset:4608
	ds_read_u16 v40, v210 offset:4640
	v_fmamk_f32 v32, v32, 0x3c800000, v235
	v_rsq_f32_e32 v32, v32
	s_waitcnt lgkmcnt(1)
	v_lshlrev_b32_e32 v36, 16, v36
	v_mul_f32_e32 v44, 0xbfb8aa3b, v36
	v_exp_f32_e32 v44, v44
	v_mul_f32_e32 v41, v41, v32
	v_mul_f32_e32 v41, v50, v41
	v_mul_f32_e32 v37, v37, v32
	v_add_f32_e32 v44, 1.0, v44
	v_rcp_f32_e32 v44, v44
	v_mul_f32_e32 v37, v49, v37
	v_mul_f32_e32 v36, v44, v36
	v_mul_f32_e32 v36, v41, v36
	v_bfe_u32 v41, v36, 16, 1
	v_add3_u32 v36, v36, v41, s73
	ds_write_b16_d16_hi v210, v36 offset:7680
	s_waitcnt lgkmcnt(1)
	v_lshlrev_b32_e32 v36, 16, v40
	v_mul_f32_e32 v40, 0xbfb8aa3b, v36
	v_exp_f32_e32 v40, v40
	s_nop 0
	v_add_f32_e32 v40, 1.0, v40
	v_rcp_f32_e32 v40, v40
	s_nop 0
	v_mul_f32_e32 v36, v40, v36
	v_mul_f32_e32 v40, v45, v32
	v_mul_f32_e32 v40, v51, v40
	v_mul_f32_e32 v36, v40, v36
	v_bfe_u32 v40, v36, 16, 1
	v_add3_u32 v36, v36, v40, s73
	ds_write_b16_d16_hi v210, v36 offset:7712
	ds_read_u16 v36, v210 offset:4672
	v_mul_f32_e32 v32, v33, v32
	v_mul_f32_e32 v32, v48, v32
	s_waitcnt lgkmcnt(0)
	v_lshlrev_b32_e32 v36, 16, v36
	v_mul_f32_e32 v40, 0xbfb8aa3b, v36
	v_exp_f32_e32 v40, v40
	s_nop 0
	v_add_f32_e32 v40, 1.0, v40
	v_rcp_f32_e32 v40, v40
	s_nop 0
	v_mul_f32_e32 v36, v40, v36
	v_mul_f32_e32 v36, v37, v36
	v_bfe_u32 v37, v36, 16, 1
	v_add3_u32 v36, v36, v37, s73
	ds_write_b16_d16_hi v210, v36 offset:7744
	ds_read_u16 v36, v210 offset:4704
	s_waitcnt lgkmcnt(0)
	v_lshlrev_b32_e32 v36, 16, v36
	v_mul_f32_e32 v37, 0xbfb8aa3b, v36
	v_exp_f32_e32 v37, v37
	s_nop 0
	v_add_f32_e32 v37, 1.0, v37
	v_rcp_f32_e32 v37, v37
	s_nop 0
	v_mul_f32_e32 v36, v37, v36
	v_mul_f32_e32 v32, v32, v36
	v_bfe_u32 v33, v32, 16, 1
	v_add3_u32 v32, v32, v33, s73
	ds_write_b16_d16_hi v210, v32 offset:7776
	v_mul_f32_e32 v32, v46, v46
	v_mul_f32_e32 v33, v34, v34
	v_fmac_f32_e32 v32, v42, v42
	v_fmac_f32_e32 v33, v38, v38
	v_add_f32_e32 v32, v32, v33
	ds_bpermute_b32 v33, v159, v32
	s_waitcnt lgkmcnt(0)
	v_add_f32_e32 v32, v32, v33
	ds_bpermute_b32 v33, v158, v32
	s_waitcnt lgkmcnt(0)
	v_add_f32_e32 v32, v32, v33
	ds_bpermute_b32 v33, v156, v32
	s_waitcnt lgkmcnt(0)
	v_add_f32_e32 v32, v32, v33
	ds_bpermute_b32 v33, v157, v32
	s_waitcnt lgkmcnt(0)
	v_add_f32_e32 v32, v32, v33
	ds_read_u16 v33, v211 offset:4608
	ds_read_u16 v36, v211 offset:4640
	v_fmamk_f32 v32, v32, 0x3c800000, v235
	v_rsq_f32_e32 v32, v32
	s_waitcnt lgkmcnt(1)
	v_lshlrev_b32_e32 v33, 16, v33
	v_mul_f32_e32 v37, 0xbfb8aa3b, v33
	v_exp_f32_e32 v37, v37
	s_nop 0
	v_add_f32_e32 v37, 1.0, v37
	v_rcp_f32_e32 v37, v37
	s_nop 0
	v_mul_f32_e32 v33, v37, v33
	v_mul_f32_e32 v37, v42, v32
	v_mul_f32_e32 v37, v50, v37
	v_mul_f32_e32 v33, v37, v33
	v_bfe_u32 v37, v33, 16, 1
	v_add3_u32 v33, v33, v37, s73
	ds_write_b16_d16_hi v211, v33 offset:7680
	s_waitcnt lgkmcnt(1)
	v_lshlrev_b32_e32 v33, 16, v36
	v_mul_f32_e32 v36, 0xbfb8aa3b, v33
	v_exp_f32_e32 v36, v36
	s_nop 0
	v_add_f32_e32 v36, 1.0, v36
	v_rcp_f32_e32 v36, v36
	s_nop 0
	v_mul_f32_e32 v33, v36, v33
	v_mul_f32_e32 v36, v46, v32
	v_mul_f32_e32 v36, v51, v36
	v_mul_f32_e32 v33, v36, v33
	v_bfe_u32 v36, v33, 16, 1
	v_add3_u32 v33, v33, v36, s73
	ds_write_b16_d16_hi v211, v33 offset:7712
	ds_read_u16 v33, v211 offset:4672
	s_waitcnt lgkmcnt(0)
	v_lshlrev_b32_e32 v33, 16, v33
	v_mul_f32_e32 v36, 0xbfb8aa3b, v33
	v_exp_f32_e32 v36, v36
	s_nop 0
	v_add_f32_e32 v36, 1.0, v36
	v_rcp_f32_e32 v36, v36
	s_nop 0
	v_mul_f32_e32 v33, v36, v33
	v_mul_f32_e32 v36, v38, v32
	v_mul_f32_e32 v36, v49, v36
	v_mul_f32_e32 v33, v36, v33
	v_bfe_u32 v36, v33, 16, 1
	v_add3_u32 v33, v33, v36, s73
	ds_write_b16_d16_hi v211, v33 offset:7744
	ds_read_u16 v33, v211 offset:4704
	v_mul_f32_e32 v32, v34, v32
	v_mul_f32_e32 v32, v48, v32
	s_waitcnt lgkmcnt(0)
	v_lshlrev_b32_e32 v33, 16, v33
	v_mul_f32_e32 v36, 0xbfb8aa3b, v33
	v_exp_f32_e32 v36, v36
	s_nop 0
	v_add_f32_e32 v36, 1.0, v36
	v_rcp_f32_e32 v36, v36
	s_nop 0
	v_mul_f32_e32 v33, v36, v33
	v_mul_f32_e32 v32, v32, v33
	v_bfe_u32 v33, v32, 16, 1
	v_add3_u32 v32, v32, v33, s73
	ds_write_b16_d16_hi v211, v32 offset:7776
	v_mul_f32_e32 v32, v47, v47
	v_mul_f32_e32 v33, v35, v35
	v_fmac_f32_e32 v32, v43, v43
	v_fmac_f32_e32 v33, v39, v39
	v_add_f32_e32 v32, v32, v33
	ds_bpermute_b32 v33, v159, v32
	s_waitcnt lgkmcnt(0)
	v_add_f32_e32 v32, v32, v33
	ds_bpermute_b32 v33, v158, v32
	s_waitcnt lgkmcnt(0)
	v_add_f32_e32 v32, v32, v33
	ds_bpermute_b32 v33, v156, v32
	s_waitcnt lgkmcnt(0)
	v_add_f32_e32 v32, v32, v33
	ds_bpermute_b32 v33, v157, v32
	s_waitcnt lgkmcnt(0)
	v_add_f32_e32 v32, v32, v33
	ds_read_u16 v33, v212 offset:4608
	ds_read_u16 v34, v212 offset:4640
	v_fmamk_f32 v32, v32, 0x3c800000, v235
	v_rsq_f32_e32 v32, v32
	s_waitcnt lgkmcnt(1)
; #define LAS __attribute__((address_space(3)))
; #define LDS_WAIT() asm volatile("s_waitcnt lgkmcnt(0)" ::: "memory")
; __device__ __forceinline__ unsigned f2bf(float f) { unsigned u = __builtin_bit_cast(unsigned, f); return (u + 0x7fffu + ((u >> 16) & 1u)) >> 16; }
; __device__ __forceinline__ float bf1(bf16 h) { return __uint_as_float(((unsigned)h) << 16); }
; __device__ __forceinline__ float siluf(float v) { return v * sigmf(v); }
; template <bool OUT> __device__ __forceinline__ void hgrn_item2(const PA& a, LAS unsigned char* lds, int layer, int bh, int c, int wave, int lane, const HRaw& raw) {
;     ...
;     __syncthreads();
;     {
;         const int rr = lane >> 3, cc = (lane & 7) * 8;
; #pragma unroll
;         for (int k = 0; k < 2; ++k) { *(LAS v4u*)(RF + (rr + 8 * k) * 72 + cc) = raw.f[k]; *(LAS v4u*)(RV + (rr + 8 * k) * 72 + cc) = raw.v[k]; if (OUT) *(LAS v4u*)(RQ + (rr + 8 * k) * 72 + cc) = raw.q[k]; }
;         LDS_WAIT();
;         const float lb = (layer == 0) ? 0.f : sigmf(a.in[4][256 + h * 64 + lane] - a.in[4][h * 64 + lane]);
;         u16 fr[16], vr[16], qr[16];
; #pragma unroll
;         for (int t = 0; t < 16; ++t) { fr[t] = RF[t * 72 + lane]; vr[t] = RV[t * 72 + lane]; if (OUT) qr[t] = RQ[t * 72 + lane]; }
;         LDS_WAIT();
;         float cum[16], kk[16]; float run = 0.f;
; #pragma unroll
;         for (int t = 0; t < 16; ++t) { const float sg = sigmf(bf1(fr[t])); const float f = lb + (1.f - lb) * sg; kk[t] = (1.f - lb) * (1.f - sg); run += fmaxf(__logf(f), -69.f); cum[t] = run; }
;     ...
;         for (int j = 0; j < 4; ++j) {
;             float ss = (o[0][j] * o[0][j] + o[1][j] * o[1][j]) + (o[2][j] * o[2][j] + o[3][j] * o[3][j]);
;             ss += __shfl_xor(ss, 1); ss += __shfl_xor(ss, 2); ss += __shfl_xor(ss, 4); ss += __shfl_xor(ss, 8);
;             const float rs = __builtin_amdgcn_rsqf(ss * (1.f / 64.f) + EPS);
; #pragma unroll
;             for (int nt = 0; nt < 4; ++nt) { const float gt = siluf(bf1(GT[(4 * q + j) * 72 + 16 * nt + l15]));
;                 OT[(4 * q + j) * 72 + 16 * nt + l15] = (bf16)f2bf(o[nt][j] * rs * gn[nt] * gt); }
;         }
;         LDS_WAIT();
;         { const int rr = lane >> 3, cc = (lane & 7) * 8; bf16* mp = (bf16*)(a.ws + WS_MIX) + (row0 + rr) * 1024 + h * 64 + cc;
;           *(v4u*)mp = *(const LAS v4u*)(OT + rr * 72 + cc); *(v4u*)(mp + 8 * 1024) = *(const LAS v4u*)(OT + (rr + 8) * 72 + cc); }
	v_lshlrev_b32_e32 v33, 16, v33
	v_mul_f32_e32 v36, 0xbfb8aa3b, v33
	v_exp_f32_e32 v36, v36
	s_nop 0
	v_add_f32_e32 v36, 1.0, v36
	v_rcp_f32_e32 v36, v36
	s_nop 0
	v_mul_f32_e32 v33, v36, v33
	v_mul_f32_e32 v36, v43, v32
	v_mul_f32_e32 v36, v50, v36
	v_mul_f32_e32 v33, v36, v33
	v_bfe_u32 v36, v33, 16, 1
	v_add3_u32 v33, v33, v36, s73
	ds_write_b16_d16_hi v212, v33 offset:7680
	s_waitcnt lgkmcnt(1)
	v_lshlrev_b32_e32 v33, 16, v34
	v_mul_f32_e32 v34, 0xbfb8aa3b, v33
	v_exp_f32_e32 v34, v34
	s_nop 0
	v_add_f32_e32 v34, 1.0, v34
	v_rcp_f32_e32 v34, v34
	s_nop 0
	v_mul_f32_e32 v33, v34, v33
	v_mul_f32_e32 v34, v47, v32
	v_mul_f32_e32 v34, v51, v34
	v_mul_f32_e32 v33, v34, v33
	v_bfe_u32 v34, v33, 16, 1
	v_add3_u32 v33, v33, v34, s73
	ds_write_b16_d16_hi v212, v33 offset:7712
	ds_read_u16 v33, v212 offset:4672
	s_waitcnt lgkmcnt(0)
	v_lshlrev_b32_e32 v33, 16, v33
	v_mul_f32_e32 v34, 0xbfb8aa3b, v33
	v_exp_f32_e32 v34, v34
	s_nop 0
	v_add_f32_e32 v34, 1.0, v34
	v_rcp_f32_e32 v34, v34
	s_nop 0
	v_mul_f32_e32 v33, v34, v33
	v_mul_f32_e32 v34, v39, v32
	v_mul_f32_e32 v34, v49, v34
	v_mul_f32_e32 v33, v34, v33
	v_bfe_u32 v34, v33, 16, 1
	v_add3_u32 v33, v33, v34, s73
	ds_write_b16_d16_hi v212, v33 offset:7744
	ds_read_u16 v33, v212 offset:4704
	v_mul_f32_e32 v32, v35, v32
	v_mul_f32_e32 v32, v48, v32
	s_waitcnt lgkmcnt(0)
	v_lshlrev_b32_e32 v33, 16, v33
	v_mul_f32_e32 v34, 0xbfb8aa3b, v33
	v_exp_f32_e32 v34, v34
	s_nop 0
	v_add_f32_e32 v34, 1.0, v34
	v_rcp_f32_e32 v34, v34
	s_nop 0
	v_mul_f32_e32 v33, v34, v33
	v_mul_f32_e32 v32, v32, v33
	v_bfe_u32 v33, v32, 16, 1
	v_add3_u32 v32, v32, v33, s73
	ds_write_b16_d16_hi v212, v32 offset:7776
	v_lshlrev_b64 v[32:33], 11, v[198:199]
	v_lshl_add_u64 v[32:33], s[90:91], 0, v[32:33]
	s_waitcnt lgkmcnt(0)
	v_lshl_add_u64 v[32:33], v[32:33], 0, s[62:63]
	v_lshl_add_u64 v[36:37], v[32:33], 0, v[220:221]
	ds_read_b128 v[32:35], v204 offset:7680
	s_waitcnt lgkmcnt(0)
	global_store_dwordx4 v[36:37], v[32:35], off
	ds_read_b128 v[32:35], v204 offset:8832
	v_add_co_u32_e32 v36, vcc, s33, v36
	s_nop 1
	v_addc_co_u32_e32 v37, vcc, 0, v37, vcc
	s_waitcnt lgkmcnt(0)
	global_store_dwordx4 v[36:37], v[32:35], off
	s_barrier
	ds_write_b128 v201, v[8:11]
	ds_write_b128 v201, v[12:15] offset:2304
	ds_write_b128 v201, v[16:19] offset:4608
	ds_write_b128 v201, v[20:23] offset:1152
	ds_write_b128 v201, v[24:27] offset:3456
	ds_write_b128 v201, v[28:31] offset:5760
	s_waitcnt lgkmcnt(0)
	v_mov_b32_e32 v8, 0
	s_and_b64 vcc, exec, s[48:49]
	v_mov_b32_e32 v19, 0
	s_cbranch_vccnz .LBB0_734
	v_lshlrev_b32_e32 v9, 5, v234
	v_add_u32_e32 v9, 0x1e000, v9
	ds_read_b32 v19, v9 offset:16
	s_waitcnt lgkmcnt(0)
.LBB0_734:
	ds_read_u16 v9, v202 offset:2304
	ds_read_u16 v10, v202 offset:2448
	ds_read_u16 v11, v202 offset:2592
	ds_read_u16 v12, v202 offset:2736
	ds_read_u16 v13, v202 offset:2880
	ds_read_u16 v14, v202 offset:3024
	ds_read_u16 v15, v202 offset:3168
	ds_read_u16 v16, v202 offset:3312
	s_waitcnt lgkmcnt(6)
	v_lshl_or_b32 v10, v10, 16, v9
	s_waitcnt lgkmcnt(4)
	v_lshl_or_b32 v11, v12, 16, v11
	s_waitcnt lgkmcnt(2)
	v_lshl_or_b32 v12, v14, 16, v13
	s_waitcnt lgkmcnt(0)
	v_lshl_or_b32 v13, v16, 16, v15
	ds_read_u16 v9, v202 offset:3456
	ds_read_u16 v14, v202 offset:3600
	ds_read_u16 v15, v202 offset:3744
	ds_read_u16 v16, v202 offset:3888
	ds_read_u16 v17, v202 offset:4032
	ds_read_u16 v18, v202 offset:4176
	ds_read_u16 v20, v202 offset:4320
	ds_read_u16 v21, v202 offset:4464
	s_waitcnt lgkmcnt(6)
	v_lshl_or_b32 v14, v14, 16, v9
	ds_read_u16 v9, v202
	ds_read_u16 v22, v202 offset:144
	ds_read_u16 v23, v202 offset:288
	ds_read_u16 v24, v202 offset:432
	ds_read_u16 v25, v202 offset:576
	ds_read_u16 v26, v202 offset:720
	ds_read_u16 v27, v202 offset:864
	ds_read_u16 v28, v202 offset:1008
	s_waitcnt lgkmcnt(7)
	v_lshlrev_b32_e32 v9, 16, v9
	v_mul_f32_e32 v9, 0xbfb8aa3b, v9
	v_exp_f32_e32 v9, v9
	v_lshl_or_b32 v15, v16, 16, v15
	v_lshl_or_b32 v16, v18, 16, v17
	v_lshl_or_b32 v17, v21, 16, v20
	v_add_f32_e32 v9, 1.0, v9
	v_rcp_f32_e32 v20, v9
	v_sub_f32_e32 v18, 1.0, v19
	s_waitcnt lgkmcnt(6)
	v_lshlrev_b32_e32 v22, 16, v22
	v_mul_f32_e32 v22, 0xbfb8aa3b, v22
	v_fma_f32 v9, v18, v20, v19
	v_cmp_gt_f32_e32 vcc, s27, v9
	v_exp_f32_e32 v22, v22
	s_waitcnt lgkmcnt(5)
	v_lshlrev_b32_e32 v23, 16, v23
	v_cndmask_b32_e64 v21, 0, 32, vcc
	v_ldexp_f32 v9, v9, v21
	v_log_f32_e32 v21, v9
	v_add_f32_e32 v22, 1.0, v22
	v_rcp_f32_e32 v22, v22
	v_mul_f32_e32 v23, 0xbfb8aa3b, v23
	v_mul_f32_e32 v34, 0x3f317217, v21
	v_fma_f32 v34, v21, s80, -v34
	v_fmac_f32_e32 v34, 0x3377d1cf, v21
	v_fmac_f32_e32 v34, 0x3f317217, v21
	v_cmp_lt_f32_e64 s[0:1], |v21|, s81
	v_fma_f32 v36, v18, v22, v19
	v_exp_f32_e32 v23, v23
	v_cndmask_b32_e64 v21, v21, v34, s[0:1]
	v_cndmask_b32_e32 v34, 0, v238, vcc
	v_cmp_gt_f32_e32 vcc, s27, v36
	v_sub_f32_e32 v21, v21, v34
	v_max_f32_e32 v21, 0xc28a0000, v21
	v_cndmask_b32_e64 v44, 0, 32, vcc
	v_ldexp_f32 v36, v36, v44
	v_log_f32_e32 v36, v36
	v_add_f32_e32 v44, 0, v21
	s_waitcnt lgkmcnt(4)
	v_lshlrev_b32_e32 v24, 16, v24
	v_mul_f32_e32 v24, 0xbfb8aa3b, v24
	v_mul_f32_e32 v21, 0x3f317217, v36
	v_fma_f32 v34, v36, s80, -v21
	v_add_f32_e32 v21, 1.0, v23
	v_rcp_f32_e32 v21, v21
	v_fmac_f32_e32 v34, 0x3377d1cf, v36
	v_fmac_f32_e32 v34, 0x3f317217, v36
	v_cmp_lt_f32_e64 s[0:1], |v36|, s81
	v_exp_f32_e32 v24, v24
	s_waitcnt lgkmcnt(3)
; __device__ __forceinline__ float bf1(bf16 h) { return __uint_as_float(((unsigned)h) << 16); }
; __device__ __forceinline__ float sigmf(float v) { return __builtin_amdgcn_rcpf(1.0f + __builtin_amdgcn_exp2f(-1.4426950408889634f * v)); }
; template <bool OUT> __device__ __forceinline__ void hgrn_item2(const PA& a, LAS unsigned char* lds, int layer, int bh, int c, int wave, int lane, const HRaw& raw) {
;     ...
;         float cum[16], kk[16]; float run = 0.f;
; #pragma unroll
;         for (int t = 0; t < 16; ++t) { const float sg = sigmf(bf1(fr[t])); const float f = lb + (1.f - lb) * sg; kk[t] = (1.f - lb) * (1.f - sg); run += fmaxf(__logf(f), -69.f); cum[t] = run; }
	v_lshlrev_b32_e32 v25, 16, v25
	v_cndmask_b32_e64 v23, v36, v34, s[0:1]
	v_fma_f32 v36, v18, v21, v19
	v_cndmask_b32_e32 v34, 0, v238, vcc
	v_cmp_gt_f32_e32 vcc, s27, v36
	v_sub_f32_e32 v23, v23, v34
	v_max_f32_e32 v23, 0xc28a0000, v23
	v_cndmask_b32_e64 v45, 0, 32, vcc
	v_ldexp_f32 v36, v36, v45
	v_log_f32_e32 v36, v36
	v_add_f32_e32 v45, v44, v23
	v_mul_f32_e32 v25, 0xbfb8aa3b, v25
	v_exp_f32_e32 v25, v25
	v_mul_f32_e32 v23, 0x3f317217, v36
	v_fma_f32 v34, v36, s80, -v23
	v_add_f32_e32 v23, 1.0, v24
	v_rcp_f32_e32 v23, v23
	v_fmac_f32_e32 v34, 0x3377d1cf, v36
	v_fmac_f32_e32 v34, 0x3f317217, v36
	v_cmp_lt_f32_e64 s[0:1], |v36|, s81
	s_waitcnt lgkmcnt(2)
	v_lshlrev_b32_e32 v26, 16, v26
	v_mul_f32_e32 v26, 0xbfb8aa3b, v26
	v_cndmask_b32_e64 v24, v36, v34, s[0:1]
	v_fma_f32 v36, v18, v23, v19
	v_cndmask_b32_e32 v34, 0, v238, vcc
	v_cmp_gt_f32_e32 vcc, s27, v36
	v_sub_f32_e32 v24, v24, v34
	v_max_f32_e32 v24, 0xc28a0000, v24
	v_cndmask_b32_e64 v46, 0, 32, vcc
	v_ldexp_f32 v36, v36, v46
	v_log_f32_e32 v36, v36
	v_add_f32_e32 v46, v45, v24
	v_exp_f32_e32 v26, v26
	s_waitcnt lgkmcnt(1)
	v_lshlrev_b32_e32 v27, 16, v27
	v_mul_f32_e32 v24, 0x3f317217, v36
	v_fma_f32 v34, v36, s80, -v24
	v_add_f32_e32 v24, 1.0, v25
	v_rcp_f32_e32 v24, v24
	v_fmac_f32_e32 v34, 0x3377d1cf, v36
	v_fmac_f32_e32 v34, 0x3f317217, v36
	v_cmp_lt_f32_e64 s[0:1], |v36|, s81
	v_add_f32_e32 v26, 1.0, v26
	v_rcp_f32_e32 v26, v26
	v_cndmask_b32_e64 v25, v36, v34, s[0:1]
	v_fma_f32 v36, v18, v24, v19
	v_cndmask_b32_e32 v34, 0, v238, vcc
	v_cmp_gt_f32_e32 vcc, s27, v36
	v_sub_f32_e32 v25, v25, v34
	v_max_f32_e32 v25, 0xc28a0000, v25
	v_cndmask_b32_e64 v47, 0, 32, vcc
	v_ldexp_f32 v36, v36, v47
	v_log_f32_e32 v36, v36
	v_add_f32_e32 v47, v46, v25
	v_cndmask_b32_e32 v34, 0, v238, vcc
	v_mul_f32_e32 v27, 0xbfb8aa3b, v27
	v_mul_f32_e32 v25, 0x3f317217, v36
	v_fma_f32 v25, v36, s80, -v25
	v_fmac_f32_e32 v25, 0x3377d1cf, v36
	v_fmac_f32_e32 v25, 0x3f317217, v36
	v_cmp_lt_f32_e64 s[0:1], |v36|, s81
	v_exp_f32_e32 v27, v27
	s_waitcnt lgkmcnt(0)
	v_lshlrev_b32_e32 v28, 16, v28
	v_cndmask_b32_e64 v25, v36, v25, s[0:1]
	v_fma_f32 v36, v18, v26, v19
	v_cmp_gt_f32_e32 vcc, s27, v36
	v_sub_f32_e32 v25, v25, v34
	v_max_f32_e32 v25, 0xc28a0000, v25
	v_cndmask_b32_e64 v48, 0, 32, vcc
	v_ldexp_f32 v36, v36, v48
	v_log_f32_e32 v36, v36
	v_add_f32_e32 v48, v47, v25
	v_mul_f32_e32 v28, 0xbfb8aa3b, v28
	v_exp_f32_e32 v28, v28
	v_mul_f32_e32 v25, 0x3f317217, v36
	v_fma_f32 v34, v36, s80, -v25
	v_add_f32_e32 v25, 1.0, v27
	v_rcp_f32_e32 v25, v25
	v_fmac_f32_e32 v34, 0x3377d1cf, v36
	v_fmac_f32_e32 v34, 0x3f317217, v36
	v_cmp_lt_f32_e64 s[0:1], |v36|, s81
	ds_read_u16 v29, v202 offset:1152
	ds_read_u16 v30, v202 offset:1296
	ds_read_u16 v31, v202 offset:1440
	ds_read_u16 v32, v202 offset:1584
	ds_read_u16 v33, v202 offset:1728
	ds_read_u16 v35, v202 offset:1872
	ds_read_u16 v53, v202 offset:2016
	ds_read_u16 v58, v202 offset:2160
	v_cndmask_b32_e64 v27, v36, v34, s[0:1]
	v_fma_f32 v36, v18, v25, v19
	v_cndmask_b32_e32 v34, 0, v238, vcc
	v_cmp_gt_f32_e32 vcc, s27, v36
	v_sub_f32_e32 v27, v27, v34
	v_max_f32_e32 v27, 0xc28a0000, v27
	v_cndmask_b32_e64 v49, 0, 32, vcc
	v_ldexp_f32 v36, v36, v49
	v_log_f32_e32 v36, v36
	v_add_f32_e32 v49, v48, v27
	s_waitcnt lgkmcnt(7)
	v_lshlrev_b32_e32 v29, 16, v29
	v_mul_f32_e32 v29, 0xbfb8aa3b, v29
	v_mul_f32_e32 v27, 0x3f317217, v36
	v_fma_f32 v34, v36, s80, -v27
	v_add_f32_e32 v27, 1.0, v28
	v_rcp_f32_e32 v27, v27
	v_fmac_f32_e32 v34, 0x3377d1cf, v36
	v_fmac_f32_e32 v34, 0x3f317217, v36
	v_cmp_lt_f32_e64 s[0:1], |v36|, s81
	v_exp_f32_e32 v29, v29
	s_waitcnt lgkmcnt(6)
	v_lshlrev_b32_e32 v30, 16, v30
	v_cndmask_b32_e64 v28, v36, v34, s[0:1]
	v_fma_f32 v36, v18, v27, v19
	v_cndmask_b32_e32 v34, 0, v238, vcc
	v_cmp_gt_f32_e32 vcc, s27, v36
	v_sub_f32_e32 v28, v28, v34
	v_max_f32_e32 v28, 0xc28a0000, v28
	v_cndmask_b32_e64 v50, 0, 32, vcc
	v_ldexp_f32 v36, v36, v50
	v_log_f32_e32 v36, v36
	v_add_f32_e32 v50, v49, v28
	v_mul_f32_e32 v30, 0xbfb8aa3b, v30
	v_exp_f32_e32 v30, v30
	v_mul_f32_e32 v28, 0x3f317217, v36
	v_fma_f32 v34, v36, s80, -v28
	v_add_f32_e32 v28, 1.0, v29
	v_rcp_f32_e32 v28, v28
	v_fmac_f32_e32 v34, 0x3377d1cf, v36
	v_fmac_f32_e32 v34, 0x3f317217, v36
	v_cmp_lt_f32_e64 s[0:1], |v36|, s81
	v_add_f32_e32 v30, 1.0, v30
	v_rcp_f32_e32 v30, v30
	v_cndmask_b32_e64 v29, v36, v34, s[0:1]
	v_fma_f32 v36, v18, v28, v19
	v_cndmask_b32_e32 v34, 0, v238, vcc
	v_cmp_gt_f32_e32 vcc, s27, v36
	v_sub_f32_e32 v29, v29, v34
	v_max_f32_e32 v29, 0xc28a0000, v29
	v_cndmask_b32_e64 v51, 0, 32, vcc
	v_ldexp_f32 v36, v36, v51
	v_log_f32_e32 v51, v36
	v_add_f32_e32 v36, v50, v29
	v_cndmask_b32_e32 v34, 0, v238, vcc
	s_waitcnt lgkmcnt(5)
	v_lshlrev_b32_e32 v31, 16, v31
	v_mul_f32_e32 v29, 0x3f317217, v51
	v_fma_f32 v29, v51, s80, -v29
	v_fmac_f32_e32 v29, 0x3377d1cf, v51
	v_fmac_f32_e32 v29, 0x3f317217, v51
	v_cmp_lt_f32_e64 s[0:1], |v51|, s81
	v_mul_f32_e32 v31, 0xbfb8aa3b, v31
	v_exp_f32_e32 v31, v31
	v_cndmask_b32_e64 v29, v51, v29, s[0:1]
	v_fma_f32 v51, v18, v30, v19
	v_cmp_gt_f32_e32 vcc, s27, v51
	v_sub_f32_e32 v29, v29, v34
	v_max_f32_e32 v29, 0xc28a0000, v29
	v_cndmask_b32_e64 v52, 0, 32, vcc
	v_ldexp_f32 v51, v51, v52
	v_log_f32_e32 v52, v51
	v_add_f32_e32 v51, v36, v29
	s_waitcnt lgkmcnt(4)
	v_lshlrev_b32_e32 v32, 16, v32
	v_mul_f32_e32 v32, 0xbfb8aa3b, v32
	v_mul_f32_e32 v29, 0x3f317217, v52
	v_fma_f32 v34, v52, s80, -v29
	v_add_f32_e32 v29, 1.0, v31
	v_rcp_f32_e32 v29, v29
	v_fmac_f32_e32 v34, 0x3377d1cf, v52
	v_fmac_f32_e32 v34, 0x3f317217, v52
	v_cmp_lt_f32_e64 s[0:1], |v52|, s81
	v_exp_f32_e32 v32, v32
	s_waitcnt lgkmcnt(3)
; __device__ __forceinline__ float bf1(bf16 h) { return __uint_as_float(((unsigned)h) << 16); }
; __device__ __forceinline__ float sigmf(float v) { return __builtin_amdgcn_rcpf(1.0f + __builtin_amdgcn_exp2f(-1.4426950408889634f * v)); }
; template <bool OUT> __device__ __forceinline__ void hgrn_item2(const PA& a, LAS unsigned char* lds, int layer, int bh, int c, int wave, int lane, const HRaw& raw) {
;     ...
;         float cum[16], kk[16]; float run = 0.f;
; #pragma unroll
;         for (int t = 0; t < 16; ++t) { const float sg = sigmf(bf1(fr[t])); const float f = lb + (1.f - lb) * sg; kk[t] = (1.f - lb) * (1.f - sg); run += fmaxf(__logf(f), -69.f); cum[t] = run; }
;         const float cl = cum[15], c7 = cum[7];
;         DL[lane] = __expf(cl);
;         if (OUT) E7L[lane] = __expf(c7); else DALL[wave * 64 + lane] = cl;
	v_lshlrev_b32_e32 v33, 16, v33
	v_cndmask_b32_e64 v31, v52, v34, s[0:1]
	v_fma_f32 v52, v18, v29, v19
	v_cndmask_b32_e32 v34, 0, v238, vcc
	v_cmp_gt_f32_e32 vcc, s27, v52
	v_sub_f32_e32 v31, v31, v34
	v_max_f32_e32 v31, 0xc28a0000, v31
	v_cndmask_b32_e64 v54, 0, 32, vcc
	v_ldexp_f32 v52, v52, v54
	v_log_f32_e32 v54, v52
	v_add_f32_e32 v52, v51, v31
	v_mul_f32_e32 v33, 0xbfb8aa3b, v33
	v_exp_f32_e32 v33, v33
	v_mul_f32_e32 v31, 0x3f317217, v54
	v_fma_f32 v34, v54, s80, -v31
	v_add_f32_e32 v31, 1.0, v32
	v_rcp_f32_e32 v31, v31
	v_fmac_f32_e32 v34, 0x3377d1cf, v54
	v_fmac_f32_e32 v34, 0x3f317217, v54
	v_cmp_lt_f32_e64 s[0:1], |v54|, s81
	v_add_f32_e32 v33, 1.0, v33
	ds_read_u16 v43, v202 offset:4608
	ds_read_u16 v42, v202 offset:4752
	ds_read_u16 v41, v202 offset:4896
	ds_read_u16 v40, v202 offset:5040
	ds_read_u16 v39, v202 offset:5184
	ds_read_u16 v38, v202 offset:5328
	ds_read_u16 v37, v202 offset:5472
	ds_read_u16 v9, v202 offset:5616
	v_cndmask_b32_e64 v32, v54, v34, s[0:1]
	v_fma_f32 v54, v18, v31, v19
	v_cndmask_b32_e32 v34, 0, v238, vcc
	v_cmp_gt_f32_e32 vcc, s27, v54
	v_sub_f32_e32 v32, v32, v34
	v_max_f32_e32 v32, 0xc28a0000, v32
	v_cndmask_b32_e64 v55, 0, 32, vcc
	v_ldexp_f32 v54, v54, v55
	v_log_f32_e32 v55, v54
	v_add_f32_e32 v54, v52, v32
	v_rcp_f32_e32 v34, v33
	v_cndmask_b32_e32 v33, 0, v238, vcc
	v_mul_f32_e32 v32, 0x3f317217, v55
	v_fma_f32 v32, v55, s80, -v32
	v_fmac_f32_e32 v32, 0x3377d1cf, v55
	v_fmac_f32_e32 v32, 0x3f317217, v55
	v_cmp_lt_f32_e64 s[0:1], |v55|, s81
	ds_read_u16 v84, v202 offset:5760
	ds_read_u16 v85, v202 offset:5904
	ds_read_u16 v86, v202 offset:6048
	ds_read_u16 v87, v202 offset:6192
	ds_read_u16 v63, v202 offset:6336
	ds_read_u16 v62, v202 offset:6480
	ds_read_u16 v61, v202 offset:6624
	ds_read_u16 v59, v202 offset:6768
	v_cndmask_b32_e64 v32, v55, v32, s[0:1]
	v_sub_f32_e32 v32, v32, v33
	s_waitcnt lgkmcnt(14)
	v_lshlrev_b32_e32 v33, 16, v35
	v_fma_f32 v55, v18, v34, v19
	v_mul_f32_e32 v33, 0xbfb8aa3b, v33
	v_cmp_gt_f32_e32 vcc, s27, v55
	v_exp_f32_e32 v33, v33
	v_max_f32_e32 v32, 0xc28a0000, v32
	v_cndmask_b32_e64 v56, 0, 32, vcc
	v_ldexp_f32 v55, v55, v56
	v_log_f32_e32 v56, v55
	v_add_f32_e32 v33, 1.0, v33
	v_rcp_f32_e32 v64, v33
	v_add_f32_e32 v55, v54, v32
	v_mul_f32_e32 v32, 0x3f317217, v56
	v_fma_f32 v32, v56, s80, -v32
	v_fmac_f32_e32 v32, 0x3377d1cf, v56
	v_fma_f32 v35, v18, v64, v19
	v_fmac_f32_e32 v32, 0x3f317217, v56
	v_cmp_lt_f32_e64 s[0:1], |v56|, s81
	v_cndmask_b32_e32 v33, 0, v238, vcc
	v_cmp_gt_f32_e32 vcc, s27, v35
	v_cndmask_b32_e64 v32, v56, v32, s[0:1]
	v_sub_f32_e32 v32, v32, v33
	v_cndmask_b32_e64 v56, 0, 32, vcc
	v_ldexp_f32 v35, v35, v56
	v_lshlrev_b32_e32 v33, 16, v53
	v_log_f32_e32 v57, v35
	v_mul_f32_e32 v33, 0xbfb8aa3b, v33
	v_exp_f32_e32 v33, v33
	v_max_f32_e32 v32, 0xc28a0000, v32
	v_add_f32_e32 v56, v55, v32
	v_mul_f32_e32 v32, 0x3f317217, v57
	v_fma_f32 v32, v57, s80, -v32
	v_add_f32_e32 v33, 1.0, v33
	v_fmac_f32_e32 v32, 0x3377d1cf, v57
	v_rcp_f32_e32 v35, v33
	v_fmac_f32_e32 v32, 0x3f317217, v57
	v_cmp_lt_f32_e64 s[0:1], |v57|, s81
	v_cndmask_b32_e32 v33, 0, v238, vcc
	v_fma_f32 v53, v18, v35, v19
	v_cndmask_b32_e64 v32, v57, v32, s[0:1]
	v_sub_f32_e32 v32, v32, v33
	v_lshlrev_b32_e32 v33, 16, v58
	v_mul_f32_e32 v33, 0xbfb8aa3b, v33
	v_cmp_gt_f32_e32 vcc, s27, v53
	v_exp_f32_e32 v33, v33
	v_max_f32_e32 v32, 0xc28a0000, v32
	v_cndmask_b32_e64 v57, 0, 32, vcc
	v_ldexp_f32 v53, v53, v57
	v_log_f32_e32 v53, v53
	v_add_f32_e32 v33, 1.0, v33
	v_rcp_f32_e32 v65, v33
	v_add_f32_e32 v57, v56, v32
	v_mul_f32_e32 v32, 0x3f317217, v53
	v_fma_f32 v32, v53, s80, -v32
	v_fmac_f32_e32 v32, 0x3377d1cf, v53
	v_fmac_f32_e32 v19, v18, v65
	v_fmac_f32_e32 v32, 0x3f317217, v53
	v_cmp_lt_f32_e64 s[0:1], |v53|, s81
	v_cndmask_b32_e32 v33, 0, v238, vcc
	v_cmp_gt_f32_e32 vcc, s27, v19
	v_cndmask_b32_e64 v32, v53, v32, s[0:1]
	v_sub_f32_e32 v32, v32, v33
	v_cndmask_b32_e64 v53, 0, 32, vcc
	v_ldexp_f32 v19, v19, v53
	v_log_f32_e32 v19, v19
	v_max_f32_e32 v32, 0xc28a0000, v32
	v_add_f32_e32 v58, v57, v32
	s_waitcnt lgkmcnt(0)
	v_mul_f32_e32 v32, 0x3f317217, v19
	v_fma_f32 v32, v19, s80, -v32
	v_fmac_f32_e32 v32, 0x3377d1cf, v19
	v_fmac_f32_e32 v32, 0x3f317217, v19
	v_cmp_lt_f32_e64 s[0:1], |v19|, s81
	v_pk_add_f32 v[20:21], v[20:21], 1.0 op_sel_hi:[1,0] neg_lo:[1,0] neg_hi:[1,0]
	v_pk_add_f32 v[24:25], v[24:25], 1.0 op_sel_hi:[1,0] neg_lo:[1,0] neg_hi:[1,0]
	v_cndmask_b32_e64 v19, v19, v32, s[0:1]
	v_cndmask_b32_e32 v32, 0, v238, vcc
	v_sub_f32_e32 v19, v19, v32
	v_max_f32_e32 v19, 0xc28a0000, v19
	v_add_f32_e32 v53, v58, v19
	v_mul_f32_e32 v19, 0x3fb8aa3b, v53
	v_mul_f32_e32 v32, 0x3fb8aa3b, v36
	v_exp_f32_e32 v19, v19
	v_exp_f32_e32 v32, v32
	v_sub_f32_e32 v60, v53, v36
	v_lshlrev_b32_e32 v43, 16, v43
	s_waitcnt lgkmcnt(8)
; #define LAS __attribute__((address_space(3)))
; __device__ __forceinline__ unsigned f2bf(float f) { unsigned u = __builtin_bit_cast(unsigned, f); return (u + 0x7fffu + ((u >> 16) & 1u)) >> 16; }
; __device__ __forceinline__ float bf1(bf16 h) { return __uint_as_float(((unsigned)h) << 16); }
; __device__ __forceinline__ float siluf(float v) { return v * sigmf(v); }
; __device__ __forceinline__ bf16x8 pk8(const float* v) { v4u w = {pk2(v[0], v[1]), pk2(v[2], v[3]), pk2(v[4], v[5]), pk2(v[6], v[7])}; return __builtin_bit_cast(bf16x8, w); }
; template <bool OUT> __device__ __forceinline__ void hgrn_item2(const PA& a, LAS unsigned char* lds, int layer, int bh, int c, int wave, int lane, const HRaw& raw) {
;     ...
;         const float cl = cum[15], c7 = cum[7];
;         DL[lane] = __expf(cl);
;         if (OUT) E7L[lane] = __expf(c7); else DALL[wave * 64 + lane] = cl;
;         float kh[16];
; #pragma unroll
;         for (int t = 0; t < 16; ++t) kh[t] = kk[t] * __expf(cl - cum[t]);
;         *(LAS bf16x8*)(KHT + lane * 24) = pk8(kh); *(LAS bf16x8*)(KHT + lane * 24 + 8) = pk8(kh + 8);
;         { v4u w0 = {(unsigned)vr[0] | ((unsigned)vr[1] << 16), (unsigned)vr[2] | ((unsigned)vr[3] << 16), (unsigned)vr[4] | ((unsigned)vr[5] << 16), (unsigned)vr[6] | ((unsigned)vr[7] << 16)};
;           v4u w1 = {(unsigned)vr[8] | ((unsigned)vr[9] << 16), (unsigned)vr[10] | ((unsigned)vr[11] << 16), (unsigned)vr[12] | ((unsigned)vr[13] << 16), (unsigned)vr[14] | ((unsigned)vr[15] << 16)};
;           *(LAS v4u*)(VT + lane * 24) = w0; *(LAS v4u*)(VT + lane * 24 + 8) = w1; }
;         if (OUT) {
; #pragma unroll
;             for (int t = 0; t < 16; ++t) {
;                 QT[t * 72 + lane] = (bf16)f2bf(siluf(bf1(qr[t])) * __expf(fminf(cum[t] - c7, 60.f)));
;                 KT[t * 72 + lane] = (bf16)f2bf(kk[t] * __expf(fminf(c7 - cum[t], 60.f)));
;             }
	v_lshlrev_b32_e32 v9, 16, v9
	ds_write2st64_b32 v203, v19, v32 offset0:45 offset1:46
	v_sub_f32_e32 v19, v53, v44
	v_mul_f32_e32 v19, 0x3fb8aa3b, v19
	v_exp_f32_e32 v32, v19
	v_sub_f32_e32 v19, v53, v45
	v_mul_f32_e32 v19, 0x3fb8aa3b, v19
	v_exp_f32_e32 v66, v19
	v_sub_f32_e32 v19, v53, v46
	v_mul_f32_e32 v19, 0x3fb8aa3b, v19
	v_exp_f32_e32 v33, v19
	v_sub_f32_e32 v19, v53, v47
	v_mul_f32_e32 v19, 0x3fb8aa3b, v19
	v_exp_f32_e32 v67, v19
	v_sub_f32_e32 v19, v53, v48
	v_mul_f32_e32 v19, 0x3fb8aa3b, v19
	v_exp_f32_e32 v68, v19
	v_sub_f32_e32 v19, v53, v49
	v_mul_f32_e32 v19, 0x3fb8aa3b, v19
	v_exp_f32_e32 v70, v19
	v_sub_f32_e32 v19, v53, v50
	v_mul_f32_e32 v19, 0x3fb8aa3b, v19
	v_exp_f32_e32 v69, v19
	v_mul_f32_e32 v19, 0x3fb8aa3b, v60
	v_exp_f32_e32 v71, v19
	v_sub_f32_e32 v19, v53, v51
	v_mul_f32_e32 v19, 0x3fb8aa3b, v19
	v_exp_f32_e32 v72, v19
	v_sub_f32_e32 v19, v53, v52
	v_mul_f32_e32 v19, 0x3fb8aa3b, v19
	v_exp_f32_e32 v74, v19
	v_sub_f32_e32 v19, v53, v54
	v_mul_f32_e32 v19, 0x3fb8aa3b, v19
	v_exp_f32_e32 v73, v19
	v_sub_f32_e32 v19, v53, v55
	v_mul_f32_e32 v19, 0x3fb8aa3b, v19
	v_exp_f32_e32 v75, v19
	v_sub_f32_e32 v19, v53, v56
	v_mul_f32_e32 v19, 0x3fb8aa3b, v19
	v_exp_f32_e32 v76, v19
	v_sub_f32_e32 v19, v53, v57
	v_mul_f32_e32 v19, 0x3fb8aa3b, v19
	v_exp_f32_e32 v78, v19
	v_sub_f32_e32 v19, v53, v58
	v_mul_f32_e32 v19, 0x3fb8aa3b, v19
	v_exp_f32_e32 v77, v19
	v_sub_f32_e32 v19, v53, v53
	v_mul_f32_e32 v19, 0x3fb8aa3b, v19
	v_pk_mul_f32 v[80:81], v[18:19], v[20:21] op_sel_hi:[0,1]
	v_pk_add_f32 v[20:21], v[22:23], 1.0 op_sel_hi:[1,0] neg_lo:[1,0] neg_hi:[1,0]
	v_exp_f32_e32 v79, v19
	v_pk_mul_f32 v[82:83], v[18:19], v[20:21] op_sel_hi:[0,1]
	v_pk_mul_f32 v[20:21], v[80:81], v[32:33]
	v_pk_mul_f32 v[32:33], v[18:19], v[24:25] op_sel_hi:[0,1]
	v_pk_add_f32 v[24:25], v[26:27], 1.0 op_sel_hi:[1,0] neg_lo:[1,0] neg_hi:[1,0]
	v_pk_mul_f32 v[22:23], v[82:83], v[66:67]
	v_pk_mul_f32 v[26:27], v[18:19], v[24:25] op_sel_hi:[0,1]
	v_pk_mul_f32 v[66:67], v[26:27], v[70:71]
	v_pk_mul_f32 v[24:25], v[32:33], v[68:69]
	v_bfe_u32 v19, v67, 16, 1
	v_bfe_u32 v68, v66, 16, 1
	v_bfe_u32 v69, v23, 16, 1
	v_bfe_u32 v70, v22, 16, 1
	v_add3_u32 v70, v22, v70, s73
	v_add3_u32 v69, v23, v69, s73
	v_add3_u32 v22, v66, v68, s73
	v_add3_u32 v19, v67, v19, s73
	v_bfe_u32 v23, v24, 16, 1
	v_bfe_u32 v66, v25, 16, 1
	v_bfe_u32 v67, v20, 16, 1
	v_bfe_u32 v68, v21, 16, 1
	v_add3_u32 v25, v25, v66, s73
	v_add3_u32 v23, v24, v23, s73
	v_add3_u32 v21, v21, v68, s73
	v_add3_u32 v20, v20, v67, s73
	v_lshrrev_b32_e32 v24, 16, v23
	v_lshrrev_b32_e32 v23, 16, v25
	v_lshrrev_b32_e32 v20, 16, v20
	v_lshrrev_b32_e32 v21, 16, v21
	v_and_or_b32 v23, v19, s26, v23
	v_and_or_b32 v22, v22, s26, v24
	v_and_or_b32 v21, v69, s26, v21
	v_and_or_b32 v20, v70, s26, v20
	ds_write_b128 v213, v[20:23] offset:4608
	v_pk_add_f32 v[20:21], v[28:29], 1.0 op_sel_hi:[1,0] neg_lo:[1,0] neg_hi:[1,0]
	s_nop 0
	v_pk_mul_f32 v[24:25], v[18:19], v[20:21] op_sel_hi:[0,1]
	v_pk_add_f32 v[20:21], v[30:31], 1.0 op_sel_hi:[1,0] neg_lo:[1,0] neg_hi:[1,0]
	v_pk_mul_f32 v[28:29], v[24:25], v[72:73]
	v_pk_mul_f32 v[22:23], v[18:19], v[20:21] op_sel_hi:[0,1]
	v_pk_add_f32 v[20:21], v[34:35], 1.0 op_sel_hi:[1,0] neg_lo:[1,0] neg_hi:[1,0]
	v_pk_add_f32 v[34:35], v[64:65], 1.0 op_sel_hi:[1,0] neg_lo:[1,0] neg_hi:[1,0]
	v_pk_mul_f32 v[20:21], v[18:19], v[20:21] op_sel_hi:[0,1]
	v_pk_mul_f32 v[18:19], v[18:19], v[34:35] op_sel_hi:[0,1]
	v_pk_mul_f32 v[64:65], v[18:19], v[78:79]
	v_pk_mul_f32 v[30:31], v[22:23], v[74:75]
	v_bfe_u32 v68, v65, 16, 1
	v_add3_u32 v65, v65, v68, s73
	v_bfe_u32 v68, v28, 16, 1
	v_bfe_u32 v67, v30, 16, 1
	v_add3_u32 v28, v28, v68, s73
	v_pk_mul_f32 v[34:35], v[20:21], v[76:77]
	v_bfe_u32 v66, v31, 16, 1
	v_bfe_u32 v69, v64, 16, 1
	v_add3_u32 v30, v30, v67, s73
	v_lshrrev_b32_e32 v28, 16, v28
	v_add3_u32 v31, v31, v66, s73
	v_add3_u32 v64, v64, v69, s73
	v_bfe_u32 v66, v34, 16, 1
	v_bfe_u32 v67, v35, 16, 1
	v_bfe_u32 v69, v29, 16, 1
	v_and_or_b32 v28, v30, s26, v28
	v_mul_f32_e32 v30, 0xbfb8aa3b, v43
	v_add3_u32 v29, v29, v69, s73
	v_add3_u32 v35, v35, v67, s73
	v_add3_u32 v34, v34, v66, s73
	v_exp_f32_e32 v66, v30
	v_lshrrev_b32_e32 v34, 16, v34
	v_lshrrev_b32_e32 v35, 16, v35
	v_lshrrev_b32_e32 v29, 16, v29
	v_and_or_b32 v29, v31, s26, v29
	v_and_or_b32 v31, v65, s26, v35
	v_and_or_b32 v30, v64, s26, v34
	ds_write_b128 v213, v[28:31] offset:4624
	v_sub_f32_e32 v29, v44, v36
	v_add_f32_e32 v28, 1.0, v66
	v_min_f32_e32 v29, 0x42700000, v29
	v_rcp_f32_e32 v28, v28
	v_mul_f32_e32 v29, 0x3fb8aa3b, v29
	v_exp_f32_e32 v29, v29
	ds_write_b128 v213, v[10:13] offset:7680
	ds_write_b128 v213, v[14:17] offset:7696
	v_mul_f32_e32 v10, v28, v43
	v_lshlrev_b32_e32 v12, 16, v42
	v_mul_f32_e32 v10, v10, v29
	v_bfe_u32 v11, v10, 16, 1
	v_add3_u32 v10, v10, v11, s73
	v_sub_f32_e32 v11, v36, v44
	v_mul_f32_e32 v13, 0xbfb8aa3b, v12
	v_min_f32_e32 v11, 0x42700000, v11
	v_exp_f32_e32 v13, v13
	v_mul_f32_e32 v11, 0x3fb8aa3b, v11
	v_exp_f32_e32 v11, v11
	v_sub_f32_e32 v14, v45, v36
	v_add_f32_e32 v13, 1.0, v13
	v_min_f32_e32 v14, 0x42700000, v14
	v_rcp_f32_e32 v13, v13
	v_mul_f32_e32 v14, 0x3fb8aa3b, v14
	ds_write_b16_d16_hi v202, v10
	v_mul_f32_e32 v10, v80, v11
	v_exp_f32_e32 v14, v14
	v_bfe_u32 v11, v10, 16, 1
	v_add3_u32 v10, v10, v11, s73
	ds_write_b16_d16_hi v202, v10 offset:2304
	v_mul_f32_e32 v10, v13, v12
	v_mul_f32_e32 v10, v10, v14
	v_bfe_u32 v11, v10, 16, 1
	v_lshlrev_b32_e32 v12, 16, v41
	v_add3_u32 v10, v10, v11, s73
	v_sub_f32_e32 v11, v36, v45
	v_mul_f32_e32 v13, 0xbfb8aa3b, v12
	v_min_f32_e32 v11, 0x42700000, v11
	v_exp_f32_e32 v13, v13
	v_mul_f32_e32 v11, 0x3fb8aa3b, v11
	v_exp_f32_e32 v11, v11
; __device__ __forceinline__ unsigned f2bf(float f) { unsigned u = __builtin_bit_cast(unsigned, f); return (u + 0x7fffu + ((u >> 16) & 1u)) >> 16; }
; __device__ __forceinline__ float bf1(bf16 h) { return __uint_as_float(((unsigned)h) << 16); }
; __device__ __forceinline__ float siluf(float v) { return v * sigmf(v); }
; template <bool OUT> __device__ __forceinline__ void hgrn_item2(const PA& a, LAS unsigned char* lds, int layer, int bh, int c, int wave, int lane, const HRaw& raw) {
;     ...
;         if (OUT) {
; #pragma unroll
;             for (int t = 0; t < 16; ++t) {
;                 QT[t * 72 + lane] = (bf16)f2bf(siluf(bf1(qr[t])) * __expf(fminf(cum[t] - c7, 60.f)));
;                 KT[t * 72 + lane] = (bf16)f2bf(kk[t] * __expf(fminf(c7 - cum[t], 60.f)));
;             }
	v_sub_f32_e32 v14, v46, v36
	v_add_f32_e32 v13, 1.0, v13
	v_min_f32_e32 v14, 0x42700000, v14
	v_rcp_f32_e32 v13, v13
	v_mul_f32_e32 v14, 0x3fb8aa3b, v14
	ds_write_b16_d16_hi v202, v10 offset:144
	v_mul_f32_e32 v10, v82, v11
	v_exp_f32_e32 v14, v14
	v_bfe_u32 v11, v10, 16, 1
	v_add3_u32 v10, v10, v11, s73
	ds_write_b16_d16_hi v202, v10 offset:2448
	v_mul_f32_e32 v10, v13, v12
	v_mul_f32_e32 v10, v10, v14
	v_bfe_u32 v11, v10, 16, 1
	v_lshlrev_b32_e32 v12, 16, v40
	v_add3_u32 v10, v10, v11, s73
	v_sub_f32_e32 v11, v36, v46
	v_mul_f32_e32 v13, 0xbfb8aa3b, v12
	v_min_f32_e32 v11, 0x42700000, v11
	v_exp_f32_e32 v13, v13
	v_mul_f32_e32 v11, 0x3fb8aa3b, v11
	v_exp_f32_e32 v11, v11
	v_sub_f32_e32 v14, v47, v36
	v_add_f32_e32 v13, 1.0, v13
	v_min_f32_e32 v14, 0x42700000, v14
	v_rcp_f32_e32 v13, v13
	v_mul_f32_e32 v14, 0x3fb8aa3b, v14
	ds_write_b16_d16_hi v202, v10 offset:288
	v_mul_f32_e32 v10, v81, v11
	v_exp_f32_e32 v14, v14
	v_bfe_u32 v11, v10, 16, 1
	v_add3_u32 v10, v10, v11, s73
	ds_write_b16_d16_hi v202, v10 offset:2592
	v_mul_f32_e32 v10, v13, v12
	v_mul_f32_e32 v10, v10, v14
	v_bfe_u32 v11, v10, 16, 1
	v_lshlrev_b32_e32 v12, 16, v39
	v_add3_u32 v10, v10, v11, s73
	v_sub_f32_e32 v11, v36, v47
	v_mul_f32_e32 v13, 0xbfb8aa3b, v12
	v_min_f32_e32 v11, 0x42700000, v11
	v_exp_f32_e32 v13, v13
	v_mul_f32_e32 v11, 0x3fb8aa3b, v11
	v_exp_f32_e32 v11, v11
	v_sub_f32_e32 v14, v48, v36
	v_add_f32_e32 v13, 1.0, v13
	v_min_f32_e32 v14, 0x42700000, v14
	v_rcp_f32_e32 v13, v13
	v_mul_f32_e32 v14, 0x3fb8aa3b, v14
	ds_write_b16_d16_hi v202, v10 offset:432
	v_mul_f32_e32 v10, v83, v11
	v_exp_f32_e32 v14, v14
	v_bfe_u32 v11, v10, 16, 1
	v_add3_u32 v10, v10, v11, s73
	ds_write_b16_d16_hi v202, v10 offset:2736
	v_mul_f32_e32 v10, v13, v12
	v_mul_f32_e32 v10, v10, v14
	v_bfe_u32 v11, v10, 16, 1
	v_lshlrev_b32_e32 v12, 16, v38
	v_add3_u32 v10, v10, v11, s73
	v_sub_f32_e32 v11, v36, v48
	v_mul_f32_e32 v13, 0xbfb8aa3b, v12
	v_min_f32_e32 v11, 0x42700000, v11
	v_exp_f32_e32 v13, v13
	v_mul_f32_e32 v11, 0x3fb8aa3b, v11
	v_exp_f32_e32 v11, v11
	v_sub_f32_e32 v14, v49, v36
	v_add_f32_e32 v13, 1.0, v13
	v_min_f32_e32 v14, 0x42700000, v14
	v_rcp_f32_e32 v13, v13
	v_mul_f32_e32 v14, 0x3fb8aa3b, v14
	ds_write_b16_d16_hi v202, v10 offset:576
	v_mul_f32_e32 v10, v32, v11
	v_exp_f32_e32 v14, v14
	v_bfe_u32 v11, v10, 16, 1
	v_add3_u32 v10, v10, v11, s73
	ds_write_b16_d16_hi v202, v10 offset:2880
	v_mul_f32_e32 v10, v13, v12
	v_mul_f32_e32 v10, v10, v14
	v_bfe_u32 v11, v10, 16, 1
	v_lshlrev_b32_e32 v12, 16, v37
	v_add3_u32 v10, v10, v11, s73
	v_sub_f32_e32 v11, v36, v49
	v_mul_f32_e32 v13, 0xbfb8aa3b, v12
	v_min_f32_e32 v11, 0x42700000, v11
	v_exp_f32_e32 v13, v13
	v_mul_f32_e32 v11, 0x3fb8aa3b, v11
	v_exp_f32_e32 v11, v11
	v_sub_f32_e32 v14, v50, v36
	v_add_f32_e32 v13, 1.0, v13
	v_min_f32_e32 v14, 0x42700000, v14
	v_rcp_f32_e32 v13, v13
	v_mul_f32_e32 v14, 0x3fb8aa3b, v14
	ds_write_b16_d16_hi v202, v10 offset:720
	v_mul_f32_e32 v10, v26, v11
	v_exp_f32_e32 v14, v14
	v_bfe_u32 v11, v10, 16, 1
	v_add3_u32 v10, v10, v11, s73
	ds_write_b16_d16_hi v202, v10 offset:3024
	v_mul_f32_e32 v10, v13, v12
	v_mul_f32_e32 v10, v10, v14
	v_mul_f32_e32 v12, 0xbfb8aa3b, v9
	v_bfe_u32 v11, v10, 16, 1
	v_exp_f32_e32 v12, v12
	v_add3_u32 v10, v10, v11, s73
	v_sub_f32_e32 v11, v36, v50
	v_min_f32_e32 v11, 0x42700000, v11
	v_mul_f32_e32 v11, 0x3fb8aa3b, v11
	v_sub_f32_e32 v13, v36, v36
	v_exp_f32_e32 v11, v11
	v_add_f32_e32 v12, 1.0, v12
	v_min_f32_e32 v13, 0x42700000, v13
	v_rcp_f32_e32 v12, v12
	v_mul_f32_e32 v13, 0x3fb8aa3b, v13
	v_exp_f32_e32 v13, v13
	ds_write_b16_d16_hi v202, v10 offset:864
	v_mul_f32_e32 v10, v33, v11
	v_bfe_u32 v11, v10, 16, 1
	v_mul_f32_e32 v9, v12, v9
	v_add3_u32 v10, v10, v11, s73
	v_mul_f32_e32 v9, v9, v13
	ds_write_b16_d16_hi v202, v10 offset:3168
	v_bfe_u32 v10, v9, 16, 1
	v_add3_u32 v9, v9, v10, s73
	s_waitcnt lgkmcnt(14)
	v_lshlrev_b32_e32 v10, 16, v84
	v_mul_f32_e32 v11, 0xbfb8aa3b, v10
	v_exp_f32_e32 v11, v11
	ds_write_b16_d16_hi v202, v9 offset:1008
	v_mul_f32_e32 v9, v27, v13
	v_sub_f32_e32 v13, v51, v36
	v_add_f32_e32 v11, 1.0, v11
	v_min_f32_e32 v13, 0x42700000, v13
	v_rcp_f32_e32 v11, v11
	v_mul_f32_e32 v13, 0x3fb8aa3b, v13
	v_exp_f32_e32 v13, v13
	v_bfe_u32 v12, v9, 16, 1
	v_add3_u32 v9, v9, v12, s73
	ds_write_b16_d16_hi v202, v9 offset:3312
	v_mul_f32_e32 v9, v11, v10
	v_mul_f32_e32 v9, v9, v13
	v_bfe_u32 v10, v9, 16, 1
	v_lshlrev_b32_e32 v11, 16, v85
	v_add3_u32 v9, v9, v10, s73
	v_sub_f32_e32 v10, v36, v51
	v_mul_f32_e32 v12, 0xbfb8aa3b, v11
	v_min_f32_e32 v10, 0x42700000, v10
	v_exp_f32_e32 v12, v12
	v_mul_f32_e32 v10, 0x3fb8aa3b, v10
	v_exp_f32_e32 v10, v10
	v_sub_f32_e32 v13, v52, v36
	v_add_f32_e32 v12, 1.0, v12
	v_min_f32_e32 v13, 0x42700000, v13
	v_rcp_f32_e32 v12, v12
	v_mul_f32_e32 v13, 0x3fb8aa3b, v13
	ds_write_b16_d16_hi v202, v9 offset:1152
	v_mul_f32_e32 v9, v24, v10
	v_exp_f32_e32 v13, v13
	v_bfe_u32 v10, v9, 16, 1
	v_add3_u32 v9, v9, v10, s73
	ds_write_b16_d16_hi v202, v9 offset:3456
	v_mul_f32_e32 v9, v12, v11
	v_mul_f32_e32 v9, v9, v13
	v_bfe_u32 v10, v9, 16, 1
	v_lshlrev_b32_e32 v11, 16, v86
	v_add3_u32 v9, v9, v10, s73
	v_sub_f32_e32 v10, v36, v52
	v_mul_f32_e32 v12, 0xbfb8aa3b, v11
	v_min_f32_e32 v10, 0x42700000, v10
	v_exp_f32_e32 v12, v12
	v_mul_f32_e32 v10, 0x3fb8aa3b, v10
	v_exp_f32_e32 v10, v10
	v_sub_f32_e32 v13, v54, v36
	v_add_f32_e32 v12, 1.0, v12
	v_min_f32_e32 v13, 0x42700000, v13
	v_rcp_f32_e32 v12, v12
	v_mul_f32_e32 v13, 0x3fb8aa3b, v13
	ds_write_b16_d16_hi v202, v9 offset:1296
	v_mul_f32_e32 v9, v22, v10
	v_exp_f32_e32 v13, v13
	v_bfe_u32 v10, v9, 16, 1
	v_add3_u32 v9, v9, v10, s73
	ds_write_b16_d16_hi v202, v9 offset:3600
; #define LDS_WAIT() asm volatile("s_waitcnt lgkmcnt(0)" ::: "memory")
; __device__ __forceinline__ unsigned f2bf(float f) { unsigned u = __builtin_bit_cast(unsigned, f); return (u + 0x7fffu + ((u >> 16) & 1u)) >> 16; }
; __device__ __forceinline__ float bf1(bf16 h) { return __uint_as_float(((unsigned)h) << 16); }
; __device__ __forceinline__ float siluf(float v) { return v * sigmf(v); }
; template <bool OUT> __device__ __forceinline__ void hgrn_item2(const PA& a, LAS unsigned char* lds, int layer, int bh, int c, int wave, int lane, const HRaw& raw) {
;     ...
;         if (OUT) {
; #pragma unroll
;             for (int t = 0; t < 16; ++t) {
;                 QT[t * 72 + lane] = (bf16)f2bf(siluf(bf1(qr[t])) * __expf(fminf(cum[t] - c7, 60.f)));
;                 KT[t * 72 + lane] = (bf16)f2bf(kk[t] * __expf(fminf(c7 - cum[t], 60.f)));
;             }
;         }
;     }
;     LDS_WAIT();
	v_mul_f32_e32 v9, v12, v11
	v_mul_f32_e32 v9, v9, v13
	v_bfe_u32 v10, v9, 16, 1
	v_lshlrev_b32_e32 v11, 16, v87
	v_add3_u32 v9, v9, v10, s73
	v_sub_f32_e32 v10, v36, v54
	v_mul_f32_e32 v12, 0xbfb8aa3b, v11
	v_min_f32_e32 v10, 0x42700000, v10
	v_exp_f32_e32 v12, v12
	v_mul_f32_e32 v10, 0x3fb8aa3b, v10
	v_exp_f32_e32 v10, v10
	v_sub_f32_e32 v13, v55, v36
	v_add_f32_e32 v12, 1.0, v12
	v_min_f32_e32 v13, 0x42700000, v13
	v_rcp_f32_e32 v12, v12
	v_mul_f32_e32 v13, 0x3fb8aa3b, v13
	ds_write_b16_d16_hi v202, v9 offset:1440
	v_mul_f32_e32 v9, v25, v10
	v_exp_f32_e32 v13, v13
	v_bfe_u32 v10, v9, 16, 1
	v_add3_u32 v9, v9, v10, s73
	ds_write_b16_d16_hi v202, v9 offset:3744
	v_mul_f32_e32 v9, v12, v11
	v_mul_f32_e32 v9, v9, v13
	v_bfe_u32 v10, v9, 16, 1
	v_lshlrev_b32_e32 v11, 16, v63
	v_add3_u32 v9, v9, v10, s73
	v_sub_f32_e32 v10, v36, v55
	v_mul_f32_e32 v12, 0xbfb8aa3b, v11
	v_min_f32_e32 v10, 0x42700000, v10
	v_exp_f32_e32 v12, v12
	v_mul_f32_e32 v10, 0x3fb8aa3b, v10
	v_exp_f32_e32 v10, v10
	v_sub_f32_e32 v13, v56, v36
	v_add_f32_e32 v12, 1.0, v12
	v_min_f32_e32 v13, 0x42700000, v13
	v_rcp_f32_e32 v12, v12
	v_mul_f32_e32 v13, 0x3fb8aa3b, v13
	ds_write_b16_d16_hi v202, v9 offset:1584
	v_mul_f32_e32 v9, v23, v10
	v_exp_f32_e32 v13, v13
	v_bfe_u32 v10, v9, 16, 1
	v_add3_u32 v9, v9, v10, s73
	ds_write_b16_d16_hi v202, v9 offset:3888
	v_mul_f32_e32 v9, v12, v11
	v_mul_f32_e32 v9, v9, v13
	v_bfe_u32 v10, v9, 16, 1
	v_lshlrev_b32_e32 v11, 16, v62
	v_add3_u32 v9, v9, v10, s73
	v_sub_f32_e32 v10, v36, v56
	v_mul_f32_e32 v12, 0xbfb8aa3b, v11
	v_min_f32_e32 v10, 0x42700000, v10
	v_exp_f32_e32 v12, v12
	v_mul_f32_e32 v10, 0x3fb8aa3b, v10
	v_exp_f32_e32 v10, v10
	v_sub_f32_e32 v13, v57, v36
	v_add_f32_e32 v12, 1.0, v12
	v_min_f32_e32 v13, 0x42700000, v13
	v_rcp_f32_e32 v12, v12
	v_mul_f32_e32 v13, 0x3fb8aa3b, v13
	ds_write_b16_d16_hi v202, v9 offset:1728
	v_mul_f32_e32 v9, v20, v10
	v_exp_f32_e32 v13, v13
	v_bfe_u32 v10, v9, 16, 1
	v_add3_u32 v9, v9, v10, s73
	ds_write_b16_d16_hi v202, v9 offset:4032
	v_mul_f32_e32 v9, v12, v11
	v_mul_f32_e32 v9, v9, v13
	v_bfe_u32 v10, v9, 16, 1
	v_lshlrev_b32_e32 v11, 16, v61
	v_add3_u32 v9, v9, v10, s73
	v_sub_f32_e32 v10, v36, v57
	v_mul_f32_e32 v12, 0xbfb8aa3b, v11
	v_min_f32_e32 v10, 0x42700000, v10
	v_exp_f32_e32 v12, v12
	v_mul_f32_e32 v10, 0x3fb8aa3b, v10
	v_exp_f32_e32 v10, v10
	v_sub_f32_e32 v13, v58, v36
	v_add_f32_e32 v12, 1.0, v12
	v_min_f32_e32 v13, 0x42700000, v13
	v_rcp_f32_e32 v12, v12
	v_mul_f32_e32 v13, 0x3fb8aa3b, v13
	ds_write_b16_d16_hi v202, v9 offset:1872
	v_mul_f32_e32 v9, v18, v10
	v_exp_f32_e32 v13, v13
	v_bfe_u32 v10, v9, 16, 1
	v_add3_u32 v9, v9, v10, s73
	ds_write_b16_d16_hi v202, v9 offset:4176
	v_mul_f32_e32 v9, v12, v11
	v_mul_f32_e32 v9, v9, v13
	v_bfe_u32 v10, v9, 16, 1
	v_add3_u32 v9, v9, v10, s73
	v_sub_f32_e32 v10, v36, v58
	v_min_f32_e32 v10, 0x42700000, v10
	v_lshlrev_b32_e32 v11, 16, v59
	v_mul_f32_e32 v10, 0x3fb8aa3b, v10
	v_mul_f32_e32 v12, 0xbfb8aa3b, v11
	v_exp_f32_e32 v10, v10
	v_exp_f32_e32 v12, v12
	ds_write_b16_d16_hi v202, v9 offset:2016
	v_min_f32_e32 v13, 0x42700000, v60
	v_mul_f32_e32 v9, v21, v10
	v_add_f32_e32 v12, 1.0, v12
	v_bfe_u32 v10, v9, 16, 1
	v_rcp_f32_e32 v12, v12
	v_mul_f32_e32 v13, 0x3fb8aa3b, v13
	v_exp_f32_e32 v13, v13
	v_add3_u32 v9, v9, v10, s73
	v_sub_f32_e32 v10, v36, v53
	v_min_f32_e32 v10, 0x42700000, v10
	v_mul_f32_e32 v10, 0x3fb8aa3b, v10
	ds_write_b16_d16_hi v202, v9 offset:4320
	v_mul_f32_e32 v9, v12, v11
	v_exp_f32_e32 v10, v10
	v_mul_f32_e32 v9, v9, v13
	v_bfe_u32 v11, v9, 16, 1
	v_add3_u32 v9, v9, v11, s73
	ds_write_b16_d16_hi v202, v9 offset:2160
	v_mul_f32_e32 v9, v19, v10
	v_bfe_u32 v10, v9, 16, 1
	v_add3_u32 v9, v9, v10, s73
	ds_write_b16_d16_hi v202, v9 offset:4464
	s_waitcnt lgkmcnt(0)
; #define LAS __attribute__((address_space(3)))
; template <bool OUT> __device__ __forceinline__ void hgrn_item2(const PA& a, LAS unsigned char* lds, int layer, int bh, int c, int wave, int lane, const HRaw& raw) {
;     ...
;     LDS_WAIT();
;     bf16x8 vfr[4];
; #pragma unroll
;     for (int nt = 0; nt < 4; ++nt) vfr[nt] = (q < 2) ? *(const LAS bf16x8*)(VT + (16 * nt + l15) * 24 + q * 8) : zero8;
;     f32x4 U[4][4];
; #pragma unroll
;     for (int mt = 0; mt < 4; ++mt) { const bf16x8 afr = (q < 2) ? *(const LAS bf16x8*)(KHT + (16 * mt + l15) * 24 + q * 8) : zero8;
; #pragma unroll
;         for (int nt = 0; nt < 4; ++nt) U[mt][nt] = __builtin_amdgcn_mfma_f32_16x16x32_bf16(afr, vfr[nt], (f32x4){0.f, 0.f, 0.f, 0.f}, 0, 0, 0); }
;     f32x4 o[4]; bf16x8 qf[2];
;     if (OUT) {
;         LDS_WAIT();
;         { const int rr = lane >> 3, cc = (lane & 7) * 8; *(LAS v4u*)(GT + rr * 72 + cc) = raw.g[0]; *(LAS v4u*)(GT + (rr + 8) * 72 + cc) = raw.g[1]; }
;         f32x4 sc = {0.f, 0.f, 0.f, 0.f};
; #pragma unroll
;         for (int ks = 0; ks < 2; ++ks) {
;             const v2u qa = *(const LAS v2u*)(QT + l15 * 72 + 32 * ks + 4 * q), qb = *(const LAS v2u*)(QT + l15 * 72 + 32 * ks + 16 + 4 * q);
;             const v2u ka = *(const LAS v2u*)(KT + l15 * 72 + 32 * ks + 4 * q), kb = *(const LAS v2u*)(KT + l15 * 72 + 32 * ks + 16 + 4 * q);
;             qf[ks] = __builtin_bit_cast(bf16x8, (v4u){qa.x, qa.y, qb.x, qb.y});
;             const bf16x8 kf = __builtin_bit_cast(bf16x8, (v4u){ka.x, ka.y, kb.x, kb.y});
;             sc = __builtin_amdgcn_mfma_f32_16x16x32_bf16(qf[ks], kf, sc, 0, 0, 0);
;         }
; #pragma unroll
;         for (int j = 0; j < 4; ++j) { const int t = 4 * q + j; P[t * 24 + l15] = (bf16)f2bf((l15 <= t) ? sc[j] : 0.f); }
;         LDS_WAIT();
;         const bf16x8 pf = (q < 2) ? *(const LAS bf16x8*)(P + l15 * 24 + q * 8) : zero8;
; #pragma unroll
;         for (int nt = 0; nt < 4; ++nt) o[nt] = __builtin_amdgcn_mfma_f32_16x16x32_bf16(pf, vfr[nt], (f32x4){0.f, 0.f, 0.f, 0.f}, 0, 0, 0);
;     }
;     {
;         float S8[8];
; #pragma unroll
;         for (int i = 0; i < 8; ++i) S8[i] = 0.f;
;         if (OUT) {
;             const f32x4 h0 = *(const f32x4*)(HU + (size_t)item * 4096 + (size_t)((2 * wave) * 64 + lane) * 4), h1 = *(const f32x4*)(HU + (size_t)item * 4096 + (size_t)((2 * wave + 1) * 64 + lane) * 4);
	v_mov_b32_e32 v9, 0
	v_mov_b32_e32 v10, 0
	v_mov_b32_e32 v11, 0
	s_and_saveexec_b64 s[0:1], s[38:39]
	v_readlane_b32 s48, v254, 16
	v_readlane_b32 s49, v254, 17
	ds_read_b128 v[8:11], v214 offset:7680
	s_or_b64 exec, exec, s[0:1]
	v_mov_b32_e32 v92, 0
	v_mov_b32_e32 v12, 0
	v_mov_b32_e32 v13, 0
	v_mov_b32_e32 v14, 0
	v_mov_b32_e32 v15, 0
	s_and_saveexec_b64 s[0:1], s[38:39]
	ds_read_b128 v[12:15], v215 offset:7680
	s_or_b64 exec, exec, s[0:1]
	v_mov_b32_e32 v93, 0
	v_mov_b32_e32 v94, 0
	v_mov_b32_e32 v95, 0
	s_and_saveexec_b64 s[0:1], s[38:39]
	ds_read_b128 v[92:95], v214 offset:9216
	s_or_b64 exec, exec, s[0:1]
	v_mov_b32_e32 v16, 0
	v_mov_b32_e32 v20, 0
	v_mov_b32_e32 v21, 0
	v_mov_b32_e32 v22, 0
	v_mov_b32_e32 v23, 0
	s_and_saveexec_b64 s[0:1], s[38:39]
	ds_read_b128 v[20:23], v216 offset:7680
	s_or_b64 exec, exec, s[0:1]
	v_mov_b32_e32 v17, 0
	v_mov_b32_e32 v18, 0
	v_mov_b32_e32 v19, 0
	s_and_saveexec_b64 s[0:1], s[38:39]
	ds_read_b128 v[16:19], v214 offset:4608
	s_or_b64 exec, exec, s[0:1]
	s_waitcnt lgkmcnt(0)
	v_mfma_f32_16x16x32_bf16 v[24:27], v[16:19], v[8:11], 0
	v_mov_b32_e32 v52, 0
	v_mov_b32_e32 v53, 0
	v_mov_b32_e32 v54, 0
	v_mfma_f32_16x16x32_bf16 v[28:31], v[16:19], v[12:15], 0
	v_mov_b32_e32 v55, 0
	v_mfma_f32_16x16x32_bf16 v[32:35], v[16:19], v[92:95], 0
	v_mfma_f32_16x16x32_bf16 v[36:39], v[16:19], v[20:23], 0
	v_mov_b32_e32 v16, 0
	s_and_saveexec_b64 s[0:1], s[38:39]
	ds_read_b128 v[52:55], v215 offset:4608
	s_or_b64 exec, exec, s[0:1]
	s_waitcnt lgkmcnt(0)
	v_mfma_f32_16x16x32_bf16 v[40:43], v[52:55], v[8:11], 0
	v_mov_b32_e32 v17, 0
	v_mov_b32_e32 v18, 0
	v_mov_b32_e32 v19, 0
	v_mfma_f32_16x16x32_bf16 v[44:47], v[52:55], v[12:15], 0
	v_mfma_f32_16x16x32_bf16 v[48:51], v[52:55], v[92:95], 0
	v_mfma_f32_16x16x32_bf16 v[52:55], v[52:55], v[20:23], 0
	s_and_saveexec_b64 s[0:1], s[38:39]
	ds_read_b128 v[16:19], v214 offset:6144
	s_or_b64 exec, exec, s[0:1]
	s_waitcnt lgkmcnt(0)
	v_mfma_f32_16x16x32_bf16 v[56:59], v[16:19], v[8:11], 0
	v_mov_b32_e32 v72, 0
	v_mov_b32_e32 v88, 0
	v_mov_b32_e32 v89, 0
	v_mfma_f32_16x16x32_bf16 v[60:63], v[16:19], v[12:15], 0
	v_mov_b32_e32 v90, 0
	v_mov_b32_e32 v91, 0
	v_mfma_f32_16x16x32_bf16 v[64:67], v[16:19], v[92:95], 0
	v_mfma_f32_16x16x32_bf16 v[68:71], v[16:19], v[20:23], 0
	s_and_saveexec_b64 s[0:1], s[38:39]
	ds_read_b128 v[88:91], v216 offset:4608
	s_or_b64 exec, exec, s[0:1]
	s_waitcnt lgkmcnt(0)
	ds_write_b128 v204, v[0:3] offset:4608
	ds_write_b128 v204, v[4:7] offset:5760
	ds_read2_b64 v[16:19], v205 offset1:4
	ds_read2_b64 v[4:7], v236 offset0:32 offset1:36
	ds_read2_b64 v[0:3], v205 offset0:8 offset1:12
	ds_read2_b64 v[84:87], v236 offset0:40 offset1:44
	s_waitcnt lgkmcnt(2)
	v_mfma_f32_16x16x32_bf16 v[4:7], v[16:19], v[4:7], 0
	s_mov_b32 s10, 0
	s_waitcnt lgkmcnt(0)
	v_mfma_f32_16x16x32_bf16 v[4:7], v[0:3], v[84:87], v[4:7]
	v_mfma_f32_16x16x32_bf16 v[76:79], v[88:91], v[8:11], 0
	s_nop 6
	v_cndmask_b32_e64 v4, v4, 0, s[40:41]
	v_cndmask_b32_e64 v5, v5, 0, s[42:43]
	v_cndmask_b32_e64 v6, v6, 0, s[44:45]
	v_bfe_u32 v73, v4, 16, 1
	v_bfe_u32 v74, v5, 16, 1
	v_bfe_u32 v75, v6, 16, 1
	v_add3_u32 v4, v4, v73, s73
	v_add3_u32 v5, v5, v74, s73
	ds_write_b16_d16_hi v217, v4 offset:10752
	ds_write_b16_d16_hi v217, v5 offset:10800
	v_add3_u32 v4, v6, v75, s73
	ds_write_b16_d16_hi v217, v4 offset:10848
	v_cndmask_b32_e64 v4, v7, 0, s[46:47]
	v_bfe_u32 v5, v4, 16, 1
	v_add3_u32 v4, v4, v5, s73
	v_mfma_f32_16x16x32_bf16 v[80:83], v[88:91], v[12:15], 0
	ds_write_b16_d16_hi v218, v4 offset:10752
	s_waitcnt lgkmcnt(0)
	v_mov_b32_e32 v73, 0
	v_mfma_f32_16x16x32_bf16 v[84:87], v[88:91], v[92:95], 0
	v_mov_b32_e32 v74, 0
	v_mov_b32_e32 v75, 0
	v_mfma_f32_16x16x32_bf16 v[88:91], v[88:91], v[20:23], 0
	s_and_saveexec_b64 s[0:1], s[38:39]
	ds_read_b128 v[72:75], v219 offset:10752
	s_or_b64 exec, exec, s[0:1]
	s_or_b32 s0, s11, s9
	s_ashr_i32 s1, s0, 31
	s_lshl_b64 s[0:1], s[0:1], 14
	s_add_u32 s0, s89, s0
	s_addc_u32 s1, s25, s1
	s_waitcnt lgkmcnt(0)
	v_mfma_f32_16x16x32_bf16 v[8:11], v[72:75], v[8:11], 0
	s_waitcnt vmcnt(0)
	v_mfma_f32_16x16x32_bf16 v[4:7], v[72:75], v[92:95], 0
	s_waitcnt lgkmcnt(0)
	s_barrier
	s_branch .LBB0_754
